# residual-add GEMM epilogues: residual rows requested two rows ahead (three register sets)
# baseline (speedup 1.0000x reference)
.LBB0_313:
	v_and_b32_e32 v140, 64, v197
	v_xor_b32_e32 v139, 16, v197
	v_add_u32_e32 v140, 64, v140
	v_cmp_lt_i32_e32 vcc, v139, v140
	v_lshl_add_u32 v138, s46, 8, v142
	v_lshl_or_b32 v136, s45, 8, v144
	v_cndmask_b32_e32 v139, v197, v139, vcc
	v_lshlrev_b32_e32 v162, 2, v139
	v_xor_b32_e32 v139, 32, v197
	v_cmp_lt_i32_e32 vcc, v139, v140
	v_ashrrev_i32_e32 v137, 31, v136
	s_lshl_b32 s20, s45, 2
	v_cndmask_b32_e32 v139, v197, v139, vcc
	v_lshlrev_b32_e32 v160, 2, v139
	v_ashrrev_i32_e32 v139, 31, v138
	v_lshlrev_b64 v[140:141], 10, v[138:139]
	v_lshl_add_u64 v[168:169], v[140:141], 0, v[136:137]
	v_lshl_add_u64 v[140:141], v[168:169], 2, s[4:5]
	v_mov_b64_e32 v[204:205], v[140:141]
	global_load_dwordx4 v[208:211], v[204:205], off
	global_load_dwordx4 v[212:215], v[204:205], off offset:64
	global_load_dwordx4 v[216:219], v[204:205], off offset:512
	global_load_dwordx4 v[220:223], v[204:205], off offset:576
	s_mov_b64 s[22:23], 0x10000
	v_lshl_add_u64 v[206:207], v[204:205], 0, s[22:23]
	global_load_dwordx4 v[224:227], v[206:207], off
	global_load_dwordx4 v[228:231], v[206:207], off offset:64
	global_load_dwordx4 v[232:235], v[206:207], off offset:512
	global_load_dwordx4 v[236:239], v[206:207], off offset:576
	s_mov_b64 s[22:23], 0x20000
	v_lshl_add_u64 v[206:207], v[204:205], 0, s[22:23]
	global_load_dwordx4 v[170:173], v[206:207], off
	global_load_dwordx4 v[174:177], v[206:207], off offset:64
	global_load_dwordx4 v[186:189], v[206:207], off offset:512
	global_load_dwordx4 v[240:243], v[206:207], off offset:576
	s_ashr_i32 s21, s20, 31
	s_waitcnt vmcnt(11)
	v_mov_b64_e32 v[164:165], v[208:209]
	v_mov_b64_e32 v[166:167], v[210:211]
	v_pk_fma_f32 v[166:167], v[128:129], 0.5, v[166:167] op_sel_hi:[1,0,1]
	v_pk_fma_f32 v[164:165], v[126:127], 0.5, v[164:165] op_sel_hi:[1,0,1]
	v_lshlrev_b64 v[126:127], 1, v[168:169]
	v_cvt_pk_bf16_f32 v128, v164, v165
	v_cvt_pk_bf16_f32 v129, v166, v167
	v_lshl_add_u64 v[168:169], s[14:15], 0, v[126:127]
	global_store_dwordx4 v[140:141], v[164:167], off
	global_store_dwordx2 v[168:169], v[128:129], off
	v_mul_f32_e32 v128, v165, v165
	v_mul_f32_e32 v129, v167, v167
	v_fmac_f32_e32 v128, v164, v164
	v_fmac_f32_e32 v129, v166, v166
	v_add_f32_e32 v163, v128, v129
	s_waitcnt vmcnt(12)
	v_mov_b64_e32 v[164:165], v[212:213]
	v_mov_b64_e32 v[166:167], v[214:215]
	v_pk_fma_f32 v[124:125], v[124:125], 0.5, v[166:167] op_sel_hi:[1,0,1]
	v_pk_fma_f32 v[122:123], v[122:123], 0.5, v[164:165] op_sel_hi:[1,0,1]
	global_store_dwordx4 v[140:141], v[122:125], off offset:64
	v_cvt_pk_bf16_f32 v128, v122, v123
	v_or_b32_e32 v164, 32, v126
	v_mul_f32_e32 v123, v123, v123
	v_mov_b32_e32 v165, v127
	v_fmac_f32_e32 v123, v122, v122
	v_mul_f32_e32 v122, v125, v125
	v_cvt_pk_bf16_f32 v129, v124, v125
	v_lshl_add_u64 v[164:165], s[14:15], 0, v[164:165]
	v_fmac_f32_e32 v122, v124, v124
	global_store_dwordx2 v[164:165], v[128:129], off
	v_add_f32_e32 v122, v123, v122
	v_add_f32_e32 v128, v163, v122
	s_waitcnt vmcnt(13)
	v_mov_b64_e32 v[122:123], v[216:217]
	v_mov_b64_e32 v[124:125], v[218:219]
	v_pk_fma_f32 v[120:121], v[120:121], 0.5, v[124:125] op_sel_hi:[1,0,1]
	v_pk_fma_f32 v[118:119], v[118:119], 0.5, v[122:123] op_sel_hi:[1,0,1]
	global_store_dwordx4 v[140:141], v[118:121], off offset:512
	v_cvt_pk_bf16_f32 v122, v118, v119
	v_or_b32_e32 v124, 0x100, v126
	v_mul_f32_e32 v119, v119, v119
	v_mov_b32_e32 v125, v127
	v_fmac_f32_e32 v119, v118, v118
	v_mul_f32_e32 v118, v121, v121
	v_cvt_pk_bf16_f32 v123, v120, v121
	v_lshl_add_u64 v[124:125], s[14:15], 0, v[124:125]
	v_fmac_f32_e32 v118, v120, v120
	global_store_dwordx2 v[124:125], v[122:123], off
	v_add_f32_e32 v118, v119, v118
	v_add_f32_e32 v122, v128, v118
	v_or_b32_e32 v126, 0x120, v126
	s_waitcnt vmcnt(14)
	v_mov_b64_e32 v[118:119], v[220:221]
	v_mov_b64_e32 v[120:121], v[222:223]
	v_pk_fma_f32 v[116:117], v[116:117], 0.5, v[120:121] op_sel_hi:[1,0,1]
	v_pk_fma_f32 v[114:115], v[114:115], 0.5, v[118:119] op_sel_hi:[1,0,1]
	global_store_dwordx4 v[140:141], v[114:117], off offset:576
	v_cvt_pk_bf16_f32 v118, v114, v115
	v_cvt_pk_bf16_f32 v119, v116, v117
	v_mul_f32_e32 v115, v115, v115
	v_fmac_f32_e32 v115, v114, v114
	v_mul_f32_e32 v114, v117, v117
	v_fmac_f32_e32 v114, v116, v116
	v_add_f32_e32 v114, v115, v114
	v_add_f32_e32 v114, v122, v114
	ds_bpermute_b32 v115, v162, v114
	v_lshl_add_u64 v[120:121], s[14:15], 0, v[126:127]
	global_store_dwordx2 v[120:121], v[118:119], off
	s_waitcnt lgkmcnt(0)
	v_add_f32_e32 v114, v114, v115
	ds_bpermute_b32 v115, v160, v114
	s_and_saveexec_b64 s[22:23], s[8:9]
	s_cbranch_execz .LBB0_315
	v_lshlrev_b64 v[116:117], 6, v[138:139]
	v_lshl_add_u64 v[116:117], s[66:67], 0, v[116:117]
	v_lshl_add_u64 v[116:117], s[20:21], 2, v[116:117]
	s_lshl_b32 s68, s39, 2
	v_lshl_add_u64 v[116:117], v[116:117], 0, s[68:69]
	s_waitcnt lgkmcnt(0)
	v_add_f32_e32 v114, v114, v115
	global_store_dword v[116:117], v114, off
.LBB0_315:
	s_or_b64 exec, exec, s[22:23]
	v_or_b32_e32 v114, 16, v138
	s_waitcnt lgkmcnt(0)
	v_ashrrev_i32_e32 v115, 31, v114
	v_lshlrev_b64 v[116:117], 10, v[114:115]
	v_lshl_add_u64 v[122:123], v[116:117], 0, v[136:137]
	v_lshl_add_u64 v[116:117], v[122:123], 2, s[4:5]
	s_mov_b64 s[22:23], 0x30000
	v_lshl_add_u64 v[206:207], v[204:205], 0, s[22:23]
	global_load_dwordx4 v[208:211], v[206:207], off
	global_load_dwordx4 v[212:215], v[206:207], off offset:64
	global_load_dwordx4 v[216:219], v[206:207], off offset:512
	global_load_dwordx4 v[220:223], v[206:207], off offset:576
	s_waitcnt vmcnt(20)
	v_mov_b64_e32 v[118:119], v[224:225]
	v_mov_b64_e32 v[120:121], v[226:227]
	v_pk_fma_f32 v[120:121], v[112:113], 0.5, v[120:121] op_sel_hi:[1,0,1]
	v_pk_fma_f32 v[118:119], v[110:111], 0.5, v[118:119] op_sel_hi:[1,0,1]
	v_lshlrev_b64 v[110:111], 1, v[122:123]
	v_cvt_pk_bf16_f32 v112, v118, v119
	v_cvt_pk_bf16_f32 v113, v120, v121
	v_lshl_add_u64 v[122:123], s[14:15], 0, v[110:111]
	global_store_dwordx4 v[116:117], v[118:121], off
	global_store_dwordx2 v[122:123], v[112:113], off
	v_mul_f32_e32 v112, v119, v119
	v_mul_f32_e32 v113, v121, v121
	v_fmac_f32_e32 v112, v118, v118
	v_fmac_f32_e32 v113, v120, v120
	v_add_f32_e32 v122, v112, v113
	s_waitcnt vmcnt(21)
	v_mov_b64_e32 v[118:119], v[228:229]
	v_mov_b64_e32 v[120:121], v[230:231]
	v_pk_fma_f32 v[108:109], v[108:109], 0.5, v[120:121] op_sel_hi:[1,0,1]
	v_pk_fma_f32 v[106:107], v[106:107], 0.5, v[118:119] op_sel_hi:[1,0,1]
	global_store_dwordx4 v[116:117], v[106:109], off offset:64
	v_cvt_pk_bf16_f32 v112, v106, v107
	v_or_b32_e32 v118, 32, v110
	v_mul_f32_e32 v107, v107, v107
	v_mov_b32_e32 v119, v111
	v_fmac_f32_e32 v107, v106, v106
	v_mul_f32_e32 v106, v109, v109
	v_cvt_pk_bf16_f32 v113, v108, v109
	v_lshl_add_u64 v[118:119], s[14:15], 0, v[118:119]
	v_fmac_f32_e32 v106, v108, v108
	global_store_dwordx2 v[118:119], v[112:113], off
	v_add_f32_e32 v106, v107, v106
	v_add_f32_e32 v112, v122, v106
	s_waitcnt vmcnt(22)
	v_mov_b64_e32 v[106:107], v[232:233]
	v_mov_b64_e32 v[108:109], v[234:235]
	v_pk_fma_f32 v[104:105], v[104:105], 0.5, v[108:109] op_sel_hi:[1,0,1]
	v_pk_fma_f32 v[102:103], v[102:103], 0.5, v[106:107] op_sel_hi:[1,0,1]
	global_store_dwordx4 v[116:117], v[102:105], off offset:512
	v_cvt_pk_bf16_f32 v106, v102, v103
	v_or_b32_e32 v108, 0x100, v110
	v_mul_f32_e32 v103, v103, v103
	v_mov_b32_e32 v109, v111
	v_fmac_f32_e32 v103, v102, v102
	v_mul_f32_e32 v102, v105, v105
	v_cvt_pk_bf16_f32 v107, v104, v105
	v_lshl_add_u64 v[108:109], s[14:15], 0, v[108:109]
	v_fmac_f32_e32 v102, v104, v104
	global_store_dwordx2 v[108:109], v[106:107], off
	v_add_f32_e32 v102, v103, v102
	v_add_f32_e32 v106, v112, v102
	v_or_b32_e32 v110, 0x120, v110
	s_waitcnt vmcnt(23)
	v_mov_b64_e32 v[102:103], v[236:237]
	v_mov_b64_e32 v[104:105], v[238:239]
	v_pk_fma_f32 v[100:101], v[100:101], 0.5, v[104:105] op_sel_hi:[1,0,1]
	v_pk_fma_f32 v[98:99], v[98:99], 0.5, v[102:103] op_sel_hi:[1,0,1]
	global_store_dwordx4 v[116:117], v[98:101], off offset:576
	v_cvt_pk_bf16_f32 v102, v98, v99
	v_cvt_pk_bf16_f32 v103, v100, v101
	v_mul_f32_e32 v99, v99, v99
	v_fmac_f32_e32 v99, v98, v98
	v_mul_f32_e32 v98, v101, v101
	v_fmac_f32_e32 v98, v100, v100
	v_add_f32_e32 v98, v99, v98
	v_add_f32_e32 v98, v106, v98
	ds_bpermute_b32 v99, v162, v98
	v_lshl_add_u64 v[104:105], s[14:15], 0, v[110:111]
	global_store_dwordx2 v[104:105], v[102:103], off
	s_waitcnt lgkmcnt(0)
	v_add_f32_e32 v98, v98, v99
	ds_bpermute_b32 v99, v160, v98
	s_and_saveexec_b64 s[22:23], s[8:9]
	s_cbranch_execz .LBB0_317
	v_lshlrev_b64 v[100:101], 6, v[114:115]
	v_lshl_add_u64 v[100:101], s[66:67], 0, v[100:101]
	v_lshl_add_u64 v[100:101], s[20:21], 2, v[100:101]
	s_lshl_b32 s68, s39, 2
	v_lshl_add_u64 v[100:101], v[100:101], 0, s[68:69]
	s_waitcnt lgkmcnt(0)
	v_add_f32_e32 v98, v98, v99
	global_store_dword v[100:101], v98, off
.LBB0_317:
	s_or_b64 exec, exec, s[22:23]
	v_or_b32_e32 v98, 32, v138
	s_waitcnt lgkmcnt(0)
	v_ashrrev_i32_e32 v99, 31, v98
	v_lshlrev_b64 v[100:101], 10, v[98:99]
	v_lshl_add_u64 v[106:107], v[100:101], 0, v[136:137]
	v_lshl_add_u64 v[100:101], v[106:107], 2, s[4:5]
	s_mov_b64 s[22:23], 0x80000
	v_lshl_add_u64 v[206:207], v[204:205], 0, s[22:23]
	global_load_dwordx4 v[224:227], v[206:207], off
	global_load_dwordx4 v[228:231], v[206:207], off offset:64
	global_load_dwordx4 v[232:235], v[206:207], off offset:512
	global_load_dwordx4 v[236:239], v[206:207], off offset:576
	s_waitcnt vmcnt(29)
	v_mov_b64_e32 v[102:103], v[170:171]
	v_mov_b64_e32 v[104:105], v[172:173]
	v_pk_fma_f32 v[104:105], v[96:97], 0.5, v[104:105] op_sel_hi:[1,0,1]
	v_pk_fma_f32 v[102:103], v[94:95], 0.5, v[102:103] op_sel_hi:[1,0,1]
	v_lshlrev_b64 v[94:95], 1, v[106:107]
	v_cvt_pk_bf16_f32 v96, v102, v103
	v_cvt_pk_bf16_f32 v97, v104, v105
	v_lshl_add_u64 v[106:107], s[14:15], 0, v[94:95]
	global_store_dwordx4 v[100:101], v[102:105], off
	global_store_dwordx2 v[106:107], v[96:97], off
	v_mul_f32_e32 v96, v103, v103
	v_mul_f32_e32 v97, v105, v105
	v_fmac_f32_e32 v96, v102, v102
	v_fmac_f32_e32 v97, v104, v104
	v_add_f32_e32 v106, v96, v97
	s_waitcnt vmcnt(30)
	v_mov_b64_e32 v[102:103], v[174:175]
	v_mov_b64_e32 v[104:105], v[176:177]
	v_pk_fma_f32 v[92:93], v[92:93], 0.5, v[104:105] op_sel_hi:[1,0,1]
	v_pk_fma_f32 v[90:91], v[90:91], 0.5, v[102:103] op_sel_hi:[1,0,1]
	global_store_dwordx4 v[100:101], v[90:93], off offset:64
	v_cvt_pk_bf16_f32 v96, v90, v91
	v_or_b32_e32 v102, 32, v94
	v_mul_f32_e32 v91, v91, v91
	v_mov_b32_e32 v103, v95
	v_fmac_f32_e32 v91, v90, v90
	v_mul_f32_e32 v90, v93, v93
	v_cvt_pk_bf16_f32 v97, v92, v93
	v_lshl_add_u64 v[102:103], s[14:15], 0, v[102:103]
	v_fmac_f32_e32 v90, v92, v92
	global_store_dwordx2 v[102:103], v[96:97], off
	v_add_f32_e32 v90, v91, v90
	v_add_f32_e32 v96, v106, v90
	s_waitcnt vmcnt(31)
	v_mov_b64_e32 v[90:91], v[186:187]
	v_mov_b64_e32 v[92:93], v[188:189]
	v_pk_fma_f32 v[88:89], v[88:89], 0.5, v[92:93] op_sel_hi:[1,0,1]
	v_pk_fma_f32 v[86:87], v[86:87], 0.5, v[90:91] op_sel_hi:[1,0,1]
	global_store_dwordx4 v[100:101], v[86:89], off offset:512
	v_cvt_pk_bf16_f32 v90, v86, v87
	v_or_b32_e32 v92, 0x100, v94
	v_mul_f32_e32 v87, v87, v87
	v_mov_b32_e32 v93, v95
	v_fmac_f32_e32 v87, v86, v86
	v_mul_f32_e32 v86, v89, v89
	v_cvt_pk_bf16_f32 v91, v88, v89
	v_lshl_add_u64 v[92:93], s[14:15], 0, v[92:93]
	v_fmac_f32_e32 v86, v88, v88
	global_store_dwordx2 v[92:93], v[90:91], off
	v_add_f32_e32 v86, v87, v86
	v_add_f32_e32 v90, v96, v86
	v_or_b32_e32 v94, 0x120, v94
	s_waitcnt vmcnt(32)
	v_mov_b64_e32 v[86:87], v[240:241]
	v_mov_b64_e32 v[88:89], v[242:243]
	v_pk_fma_f32 v[84:85], v[84:85], 0.5, v[88:89] op_sel_hi:[1,0,1]
	v_pk_fma_f32 v[82:83], v[82:83], 0.5, v[86:87] op_sel_hi:[1,0,1]
	global_store_dwordx4 v[100:101], v[82:85], off offset:576
	v_cvt_pk_bf16_f32 v86, v82, v83
	v_cvt_pk_bf16_f32 v87, v84, v85
	v_mul_f32_e32 v83, v83, v83
	v_fmac_f32_e32 v83, v82, v82
	v_mul_f32_e32 v82, v85, v85
	v_fmac_f32_e32 v82, v84, v84
	v_add_f32_e32 v82, v83, v82
	v_add_f32_e32 v82, v90, v82
	ds_bpermute_b32 v83, v162, v82
	v_lshl_add_u64 v[88:89], s[14:15], 0, v[94:95]
	global_store_dwordx2 v[88:89], v[86:87], off
	s_waitcnt lgkmcnt(0)
	v_add_f32_e32 v82, v82, v83
	ds_bpermute_b32 v83, v160, v82
	s_and_saveexec_b64 s[22:23], s[8:9]
	s_cbranch_execz .LBB0_319
	v_lshlrev_b64 v[84:85], 6, v[98:99]
	v_lshl_add_u64 v[84:85], s[66:67], 0, v[84:85]
	v_lshl_add_u64 v[84:85], s[20:21], 2, v[84:85]
	s_lshl_b32 s68, s39, 2
	v_lshl_add_u64 v[84:85], v[84:85], 0, s[68:69]
	s_waitcnt lgkmcnt(0)
	v_add_f32_e32 v82, v82, v83
	global_store_dword v[84:85], v82, off
.LBB0_319:
	s_or_b64 exec, exec, s[22:23]
	v_or_b32_e32 v82, 48, v138
	s_waitcnt lgkmcnt(0)
	v_ashrrev_i32_e32 v83, 31, v82
	v_lshlrev_b64 v[84:85], 10, v[82:83]
	v_lshl_add_u64 v[90:91], v[84:85], 0, v[136:137]
	v_lshl_add_u64 v[84:85], v[90:91], 2, s[4:5]
	s_mov_b64 s[22:23], 0x90000
	v_lshl_add_u64 v[206:207], v[204:205], 0, s[22:23]
	global_load_dwordx4 v[170:173], v[206:207], off
	global_load_dwordx4 v[174:177], v[206:207], off offset:64
	global_load_dwordx4 v[186:189], v[206:207], off offset:512
	global_load_dwordx4 v[240:243], v[206:207], off offset:576
	s_waitcnt vmcnt(29)
	v_mov_b64_e32 v[86:87], v[208:209]
	v_mov_b64_e32 v[88:89], v[210:211]
	v_pk_fma_f32 v[88:89], v[80:81], 0.5, v[88:89] op_sel_hi:[1,0,1]
	v_pk_fma_f32 v[86:87], v[78:79], 0.5, v[86:87] op_sel_hi:[1,0,1]
	v_lshlrev_b64 v[78:79], 1, v[90:91]
	v_cvt_pk_bf16_f32 v80, v86, v87
	v_cvt_pk_bf16_f32 v81, v88, v89
	v_lshl_add_u64 v[90:91], s[14:15], 0, v[78:79]
	global_store_dwordx4 v[84:85], v[86:89], off
	global_store_dwordx2 v[90:91], v[80:81], off
	v_mul_f32_e32 v80, v87, v87
	v_mul_f32_e32 v81, v89, v89
	v_fmac_f32_e32 v80, v86, v86
	v_fmac_f32_e32 v81, v88, v88
	v_add_f32_e32 v90, v80, v81
	s_waitcnt vmcnt(30)
	v_mov_b64_e32 v[86:87], v[212:213]
	v_mov_b64_e32 v[88:89], v[214:215]
	v_pk_fma_f32 v[76:77], v[76:77], 0.5, v[88:89] op_sel_hi:[1,0,1]
	v_pk_fma_f32 v[74:75], v[74:75], 0.5, v[86:87] op_sel_hi:[1,0,1]
	global_store_dwordx4 v[84:85], v[74:77], off offset:64
	v_cvt_pk_bf16_f32 v80, v74, v75
	v_or_b32_e32 v86, 32, v78
	v_mul_f32_e32 v75, v75, v75
	v_mov_b32_e32 v87, v79
	v_fmac_f32_e32 v75, v74, v74
	v_mul_f32_e32 v74, v77, v77
	v_cvt_pk_bf16_f32 v81, v76, v77
	v_lshl_add_u64 v[86:87], s[14:15], 0, v[86:87]
	v_fmac_f32_e32 v74, v76, v76
	global_store_dwordx2 v[86:87], v[80:81], off
	v_add_f32_e32 v74, v75, v74
	v_add_f32_e32 v80, v90, v74
	s_waitcnt vmcnt(31)
	v_mov_b64_e32 v[74:75], v[216:217]
	v_mov_b64_e32 v[76:77], v[218:219]
	v_pk_fma_f32 v[72:73], v[72:73], 0.5, v[76:77] op_sel_hi:[1,0,1]
	v_pk_fma_f32 v[70:71], v[70:71], 0.5, v[74:75] op_sel_hi:[1,0,1]
	global_store_dwordx4 v[84:85], v[70:73], off offset:512
	v_cvt_pk_bf16_f32 v74, v70, v71
	v_or_b32_e32 v76, 0x100, v78
	v_mul_f32_e32 v71, v71, v71
	v_mov_b32_e32 v77, v79
	v_fmac_f32_e32 v71, v70, v70
	v_mul_f32_e32 v70, v73, v73
	v_cvt_pk_bf16_f32 v75, v72, v73
	v_lshl_add_u64 v[76:77], s[14:15], 0, v[76:77]
	v_fmac_f32_e32 v70, v72, v72
	global_store_dwordx2 v[76:77], v[74:75], off
	v_add_f32_e32 v70, v71, v70
	v_add_f32_e32 v74, v80, v70
	v_or_b32_e32 v78, 0x120, v78
	s_waitcnt vmcnt(32)
	v_mov_b64_e32 v[70:71], v[220:221]
	v_mov_b64_e32 v[72:73], v[222:223]
	v_pk_fma_f32 v[68:69], v[68:69], 0.5, v[72:73] op_sel_hi:[1,0,1]
	v_pk_fma_f32 v[66:67], v[66:67], 0.5, v[70:71] op_sel_hi:[1,0,1]
	global_store_dwordx4 v[84:85], v[66:69], off offset:576
	v_cvt_pk_bf16_f32 v70, v66, v67
	v_cvt_pk_bf16_f32 v71, v68, v69
	v_mul_f32_e32 v67, v67, v67
	v_fmac_f32_e32 v67, v66, v66
	v_mul_f32_e32 v66, v69, v69
	v_fmac_f32_e32 v66, v68, v68
	v_add_f32_e32 v66, v67, v66
	v_add_f32_e32 v66, v74, v66
	ds_bpermute_b32 v67, v162, v66
	v_lshl_add_u64 v[72:73], s[14:15], 0, v[78:79]
	global_store_dwordx2 v[72:73], v[70:71], off
	s_waitcnt lgkmcnt(0)
	v_add_f32_e32 v66, v66, v67
	ds_bpermute_b32 v67, v160, v66
	s_and_saveexec_b64 s[22:23], s[8:9]
	s_cbranch_execz .LBB0_321
	v_lshlrev_b64 v[68:69], 6, v[82:83]
	v_lshl_add_u64 v[68:69], s[66:67], 0, v[68:69]
	v_lshl_add_u64 v[68:69], s[20:21], 2, v[68:69]
	s_lshl_b32 s68, s39, 2
	v_lshl_add_u64 v[68:69], v[68:69], 0, s[68:69]
	s_waitcnt lgkmcnt(0)
	v_add_f32_e32 v66, v66, v67
	global_store_dword v[68:69], v66, off
.LBB0_321:
	s_or_b64 exec, exec, s[22:23]
	v_add_u32_e32 v66, 0x80, v138
	s_waitcnt lgkmcnt(0)
	v_ashrrev_i32_e32 v67, 31, v66
	v_lshlrev_b64 v[68:69], 10, v[66:67]
	v_lshl_add_u64 v[74:75], v[68:69], 0, v[136:137]
	v_lshl_add_u64 v[68:69], v[74:75], 2, s[4:5]
	s_mov_b64 s[22:23], 0xa0000
	v_lshl_add_u64 v[206:207], v[204:205], 0, s[22:23]
	global_load_dwordx4 v[208:211], v[206:207], off
	global_load_dwordx4 v[212:215], v[206:207], off offset:64
	global_load_dwordx4 v[216:219], v[206:207], off offset:512
	global_load_dwordx4 v[220:223], v[206:207], off offset:576
	s_waitcnt vmcnt(29)
	v_mov_b64_e32 v[70:71], v[224:225]
	v_mov_b64_e32 v[72:73], v[226:227]
	v_pk_fma_f32 v[72:73], v[64:65], 0.5, v[72:73] op_sel_hi:[1,0,1]
	v_pk_fma_f32 v[70:71], v[62:63], 0.5, v[70:71] op_sel_hi:[1,0,1]
	v_lshlrev_b64 v[62:63], 1, v[74:75]
	v_cvt_pk_bf16_f32 v64, v70, v71
	v_cvt_pk_bf16_f32 v65, v72, v73
	v_lshl_add_u64 v[74:75], s[14:15], 0, v[62:63]
	global_store_dwordx4 v[68:69], v[70:73], off
	global_store_dwordx2 v[74:75], v[64:65], off
	v_mul_f32_e32 v64, v71, v71
	v_mul_f32_e32 v65, v73, v73
	v_fmac_f32_e32 v64, v70, v70
	v_fmac_f32_e32 v65, v72, v72
	v_add_f32_e32 v74, v64, v65
	s_waitcnt vmcnt(30)
	v_mov_b64_e32 v[70:71], v[228:229]
	v_mov_b64_e32 v[72:73], v[230:231]
	v_pk_fma_f32 v[60:61], v[60:61], 0.5, v[72:73] op_sel_hi:[1,0,1]
	v_pk_fma_f32 v[58:59], v[58:59], 0.5, v[70:71] op_sel_hi:[1,0,1]
	global_store_dwordx4 v[68:69], v[58:61], off offset:64
	v_cvt_pk_bf16_f32 v64, v58, v59
	v_or_b32_e32 v70, 32, v62
	v_mul_f32_e32 v59, v59, v59
	v_mov_b32_e32 v71, v63
	v_fmac_f32_e32 v59, v58, v58
	v_mul_f32_e32 v58, v61, v61
	v_cvt_pk_bf16_f32 v65, v60, v61
	v_lshl_add_u64 v[70:71], s[14:15], 0, v[70:71]
	v_fmac_f32_e32 v58, v60, v60
	global_store_dwordx2 v[70:71], v[64:65], off
	v_add_f32_e32 v58, v59, v58
	v_add_f32_e32 v64, v74, v58
	s_waitcnt vmcnt(31)
	v_mov_b64_e32 v[58:59], v[232:233]
	v_mov_b64_e32 v[60:61], v[234:235]
	v_pk_fma_f32 v[56:57], v[56:57], 0.5, v[60:61] op_sel_hi:[1,0,1]
	v_pk_fma_f32 v[54:55], v[54:55], 0.5, v[58:59] op_sel_hi:[1,0,1]
	global_store_dwordx4 v[68:69], v[54:57], off offset:512
	v_cvt_pk_bf16_f32 v58, v54, v55
	v_or_b32_e32 v60, 0x100, v62
	v_mul_f32_e32 v55, v55, v55
	v_mov_b32_e32 v61, v63
	v_fmac_f32_e32 v55, v54, v54
	v_mul_f32_e32 v54, v57, v57
	v_cvt_pk_bf16_f32 v59, v56, v57
	v_lshl_add_u64 v[60:61], s[14:15], 0, v[60:61]
	v_fmac_f32_e32 v54, v56, v56
	global_store_dwordx2 v[60:61], v[58:59], off
	v_add_f32_e32 v54, v55, v54
	v_add_f32_e32 v58, v64, v54
	v_or_b32_e32 v62, 0x120, v62
	s_waitcnt vmcnt(32)
	v_mov_b64_e32 v[54:55], v[236:237]
	v_mov_b64_e32 v[56:57], v[238:239]
	v_pk_fma_f32 v[52:53], v[52:53], 0.5, v[56:57] op_sel_hi:[1,0,1]
	v_pk_fma_f32 v[50:51], v[50:51], 0.5, v[54:55] op_sel_hi:[1,0,1]
	global_store_dwordx4 v[68:69], v[50:53], off offset:576
	v_cvt_pk_bf16_f32 v54, v50, v51
	v_cvt_pk_bf16_f32 v55, v52, v53
	v_mul_f32_e32 v51, v51, v51
	v_fmac_f32_e32 v51, v50, v50
	v_mul_f32_e32 v50, v53, v53
	v_fmac_f32_e32 v50, v52, v52
	v_add_f32_e32 v50, v51, v50
	v_add_f32_e32 v50, v58, v50
	ds_bpermute_b32 v51, v162, v50
	v_lshl_add_u64 v[56:57], s[14:15], 0, v[62:63]
	global_store_dwordx2 v[56:57], v[54:55], off
	s_waitcnt lgkmcnt(0)
	v_add_f32_e32 v50, v50, v51
	ds_bpermute_b32 v51, v160, v50
	s_and_saveexec_b64 s[22:23], s[8:9]
	s_cbranch_execz .LBB0_323
	v_lshlrev_b64 v[52:53], 6, v[66:67]
	v_lshl_add_u64 v[52:53], s[66:67], 0, v[52:53]
	v_lshl_add_u64 v[52:53], s[20:21], 2, v[52:53]
	s_lshl_b32 s68, s39, 2
	v_lshl_add_u64 v[52:53], v[52:53], 0, s[68:69]
	s_waitcnt lgkmcnt(0)
	v_add_f32_e32 v50, v50, v51
	global_store_dword v[52:53], v50, off
.LBB0_323:
	s_or_b64 exec, exec, s[22:23]
	v_add_u32_e32 v50, 0x90, v138
	s_waitcnt lgkmcnt(0)
	v_ashrrev_i32_e32 v51, 31, v50
	v_lshlrev_b64 v[52:53], 10, v[50:51]
	v_lshl_add_u64 v[58:59], v[52:53], 0, v[136:137]
	v_lshl_add_u64 v[52:53], v[58:59], 2, s[4:5]
	s_mov_b64 s[22:23], 0xb0000
	v_lshl_add_u64 v[206:207], v[204:205], 0, s[22:23]
	global_load_dwordx4 v[224:227], v[206:207], off
	global_load_dwordx4 v[228:231], v[206:207], off offset:64
	global_load_dwordx4 v[232:235], v[206:207], off offset:512
	global_load_dwordx4 v[236:239], v[206:207], off offset:576
	s_waitcnt vmcnt(29)
	v_mov_b64_e32 v[54:55], v[170:171]
	v_mov_b64_e32 v[56:57], v[172:173]
	v_pk_fma_f32 v[56:57], v[48:49], 0.5, v[56:57] op_sel_hi:[1,0,1]
	v_pk_fma_f32 v[54:55], v[46:47], 0.5, v[54:55] op_sel_hi:[1,0,1]
	v_lshlrev_b64 v[46:47], 1, v[58:59]
	v_cvt_pk_bf16_f32 v48, v54, v55
	v_cvt_pk_bf16_f32 v49, v56, v57
	v_lshl_add_u64 v[58:59], s[14:15], 0, v[46:47]
	global_store_dwordx4 v[52:53], v[54:57], off
	global_store_dwordx2 v[58:59], v[48:49], off
	v_mul_f32_e32 v48, v55, v55
	v_mul_f32_e32 v49, v57, v57
	v_fmac_f32_e32 v48, v54, v54
	v_fmac_f32_e32 v49, v56, v56
	v_add_f32_e32 v58, v48, v49
	s_waitcnt vmcnt(30)
	v_mov_b64_e32 v[54:55], v[174:175]
	v_mov_b64_e32 v[56:57], v[176:177]
	v_pk_fma_f32 v[44:45], v[44:45], 0.5, v[56:57] op_sel_hi:[1,0,1]
	v_pk_fma_f32 v[42:43], v[42:43], 0.5, v[54:55] op_sel_hi:[1,0,1]
	global_store_dwordx4 v[52:53], v[42:45], off offset:64
	v_cvt_pk_bf16_f32 v48, v42, v43
	v_or_b32_e32 v54, 32, v46
	v_mul_f32_e32 v43, v43, v43
	v_mov_b32_e32 v55, v47
	v_fmac_f32_e32 v43, v42, v42
	v_mul_f32_e32 v42, v45, v45
	v_cvt_pk_bf16_f32 v49, v44, v45
	v_lshl_add_u64 v[54:55], s[14:15], 0, v[54:55]
	v_fmac_f32_e32 v42, v44, v44
	global_store_dwordx2 v[54:55], v[48:49], off
	v_add_f32_e32 v42, v43, v42
	v_add_f32_e32 v48, v58, v42
	s_waitcnt vmcnt(31)
	v_mov_b64_e32 v[42:43], v[186:187]
	v_mov_b64_e32 v[44:45], v[188:189]
	v_pk_fma_f32 v[40:41], v[40:41], 0.5, v[44:45] op_sel_hi:[1,0,1]
	v_pk_fma_f32 v[38:39], v[38:39], 0.5, v[42:43] op_sel_hi:[1,0,1]
	global_store_dwordx4 v[52:53], v[38:41], off offset:512
	v_cvt_pk_bf16_f32 v42, v38, v39
	v_or_b32_e32 v44, 0x100, v46
	v_mul_f32_e32 v39, v39, v39
	v_mov_b32_e32 v45, v47
	v_fmac_f32_e32 v39, v38, v38
	v_mul_f32_e32 v38, v41, v41
	v_cvt_pk_bf16_f32 v43, v40, v41
	v_lshl_add_u64 v[44:45], s[14:15], 0, v[44:45]
	v_fmac_f32_e32 v38, v40, v40
	global_store_dwordx2 v[44:45], v[42:43], off
	v_add_f32_e32 v38, v39, v38
	v_add_f32_e32 v42, v48, v38
	v_or_b32_e32 v46, 0x120, v46
	s_waitcnt vmcnt(32)
	v_mov_b64_e32 v[38:39], v[240:241]
	v_mov_b64_e32 v[40:41], v[242:243]
	v_pk_fma_f32 v[36:37], v[36:37], 0.5, v[40:41] op_sel_hi:[1,0,1]
	v_pk_fma_f32 v[34:35], v[34:35], 0.5, v[38:39] op_sel_hi:[1,0,1]
	global_store_dwordx4 v[52:53], v[34:37], off offset:576
	v_cvt_pk_bf16_f32 v38, v34, v35
	v_cvt_pk_bf16_f32 v39, v36, v37
	v_mul_f32_e32 v35, v35, v35
	v_fmac_f32_e32 v35, v34, v34
	v_mul_f32_e32 v34, v37, v37
	v_fmac_f32_e32 v34, v36, v36
	v_add_f32_e32 v34, v35, v34
	v_add_f32_e32 v34, v42, v34
	ds_bpermute_b32 v35, v162, v34
	v_lshl_add_u64 v[40:41], s[14:15], 0, v[46:47]
	global_store_dwordx2 v[40:41], v[38:39], off
	s_waitcnt lgkmcnt(0)
	v_add_f32_e32 v34, v34, v35
	ds_bpermute_b32 v35, v160, v34
	s_and_saveexec_b64 s[22:23], s[8:9]
	s_cbranch_execz .LBB0_325
	v_lshlrev_b64 v[36:37], 6, v[50:51]
	v_lshl_add_u64 v[36:37], s[66:67], 0, v[36:37]
	v_lshl_add_u64 v[36:37], s[20:21], 2, v[36:37]
	s_lshl_b32 s68, s39, 2
	v_lshl_add_u64 v[36:37], v[36:37], 0, s[68:69]
	s_waitcnt lgkmcnt(0)
	v_add_f32_e32 v34, v34, v35
	global_store_dword v[36:37], v34, off
.LBB0_325:
	s_or_b64 exec, exec, s[22:23]
	v_add_u32_e32 v34, 0xa0, v138
	s_waitcnt lgkmcnt(0)
	v_ashrrev_i32_e32 v35, 31, v34
	v_lshlrev_b64 v[36:37], 10, v[34:35]
	v_lshl_add_u64 v[42:43], v[36:37], 0, v[136:137]
	v_lshl_add_u64 v[36:37], v[42:43], 2, s[4:5]
	s_waitcnt vmcnt(25)
	v_mov_b64_e32 v[38:39], v[208:209]
	v_mov_b64_e32 v[40:41], v[210:211]
	v_pk_fma_f32 v[40:41], v[32:33], 0.5, v[40:41] op_sel_hi:[1,0,1]
	v_pk_fma_f32 v[38:39], v[30:31], 0.5, v[38:39] op_sel_hi:[1,0,1]
	v_lshlrev_b64 v[30:31], 1, v[42:43]
	v_cvt_pk_bf16_f32 v32, v38, v39
	v_cvt_pk_bf16_f32 v33, v40, v41
	v_lshl_add_u64 v[42:43], s[14:15], 0, v[30:31]
	global_store_dwordx4 v[36:37], v[38:41], off
	global_store_dwordx2 v[42:43], v[32:33], off
	v_mul_f32_e32 v32, v39, v39
	v_mul_f32_e32 v33, v41, v41
	v_fmac_f32_e32 v32, v38, v38
	v_fmac_f32_e32 v33, v40, v40
	v_add_f32_e32 v42, v32, v33
	s_waitcnt vmcnt(26)
	v_mov_b64_e32 v[38:39], v[212:213]
	v_mov_b64_e32 v[40:41], v[214:215]
	v_pk_fma_f32 v[28:29], v[28:29], 0.5, v[40:41] op_sel_hi:[1,0,1]
	v_pk_fma_f32 v[26:27], v[26:27], 0.5, v[38:39] op_sel_hi:[1,0,1]
	global_store_dwordx4 v[36:37], v[26:29], off offset:64
	v_cvt_pk_bf16_f32 v32, v26, v27
	v_or_b32_e32 v38, 32, v30
	v_mul_f32_e32 v27, v27, v27
	v_mov_b32_e32 v39, v31
	v_fmac_f32_e32 v27, v26, v26
	v_mul_f32_e32 v26, v29, v29
	v_cvt_pk_bf16_f32 v33, v28, v29
	v_lshl_add_u64 v[38:39], s[14:15], 0, v[38:39]
	v_fmac_f32_e32 v26, v28, v28
	global_store_dwordx2 v[38:39], v[32:33], off
	v_add_f32_e32 v26, v27, v26
	v_add_f32_e32 v32, v42, v26
	s_waitcnt vmcnt(27)
	v_mov_b64_e32 v[26:27], v[216:217]
	v_mov_b64_e32 v[28:29], v[218:219]
	v_pk_fma_f32 v[24:25], v[24:25], 0.5, v[28:29] op_sel_hi:[1,0,1]
	v_pk_fma_f32 v[22:23], v[22:23], 0.5, v[26:27] op_sel_hi:[1,0,1]
	global_store_dwordx4 v[36:37], v[22:25], off offset:512
	v_cvt_pk_bf16_f32 v26, v22, v23
	v_or_b32_e32 v28, 0x100, v30
	v_mul_f32_e32 v23, v23, v23
	v_mov_b32_e32 v29, v31
	v_fmac_f32_e32 v23, v22, v22
	v_mul_f32_e32 v22, v25, v25
	v_cvt_pk_bf16_f32 v27, v24, v25
	v_lshl_add_u64 v[28:29], s[14:15], 0, v[28:29]
	v_fmac_f32_e32 v22, v24, v24
	global_store_dwordx2 v[28:29], v[26:27], off
	v_add_f32_e32 v22, v23, v22
	v_add_f32_e32 v26, v32, v22
	v_or_b32_e32 v30, 0x120, v30
	s_waitcnt vmcnt(28)
	v_mov_b64_e32 v[22:23], v[220:221]
	v_mov_b64_e32 v[24:25], v[222:223]
	v_pk_fma_f32 v[20:21], v[20:21], 0.5, v[24:25] op_sel_hi:[1,0,1]
	v_pk_fma_f32 v[18:19], v[18:19], 0.5, v[22:23] op_sel_hi:[1,0,1]
	global_store_dwordx4 v[36:37], v[18:21], off offset:576
	v_cvt_pk_bf16_f32 v22, v18, v19
	v_cvt_pk_bf16_f32 v23, v20, v21
	v_mul_f32_e32 v19, v19, v19
	v_fmac_f32_e32 v19, v18, v18
	v_mul_f32_e32 v18, v21, v21
	v_fmac_f32_e32 v18, v20, v20
	v_add_f32_e32 v18, v19, v18
	v_add_f32_e32 v18, v26, v18
	ds_bpermute_b32 v19, v162, v18
	v_lshl_add_u64 v[24:25], s[14:15], 0, v[30:31]
	global_store_dwordx2 v[24:25], v[22:23], off
	s_waitcnt lgkmcnt(0)
	v_add_f32_e32 v18, v18, v19
	ds_bpermute_b32 v19, v160, v18
	s_and_saveexec_b64 s[22:23], s[8:9]
	s_cbranch_execz .LBB0_327
	v_lshlrev_b64 v[20:21], 6, v[34:35]
	v_lshl_add_u64 v[20:21], s[66:67], 0, v[20:21]
	v_lshl_add_u64 v[20:21], s[20:21], 2, v[20:21]
	s_lshl_b32 s68, s39, 2
	v_lshl_add_u64 v[20:21], v[20:21], 0, s[68:69]
	s_waitcnt lgkmcnt(0)
	v_add_f32_e32 v18, v18, v19
	global_store_dword v[20:21], v18, off
.LBB0_327:
	s_or_b64 exec, exec, s[22:23]
	v_add_u32_e32 v18, 0xb0, v138
	s_waitcnt lgkmcnt(0)
	v_ashrrev_i32_e32 v19, 31, v18
	v_lshlrev_b64 v[20:21], 10, v[18:19]
	v_lshl_add_u64 v[26:27], v[20:21], 0, v[136:137]
	v_lshl_add_u64 v[20:21], v[26:27], 2, s[4:5]
	s_waitcnt vmcnt(21)
	v_mov_b64_e32 v[22:23], v[224:225]
	v_mov_b64_e32 v[24:25], v[226:227]
	v_pk_fma_f32 v[24:25], v[16:17], 0.5, v[24:25] op_sel_hi:[1,0,1]
	v_pk_fma_f32 v[22:23], v[14:15], 0.5, v[22:23] op_sel_hi:[1,0,1]
	v_lshlrev_b64 v[14:15], 1, v[26:27]
	v_cvt_pk_bf16_f32 v16, v22, v23
	v_cvt_pk_bf16_f32 v17, v24, v25
	v_lshl_add_u64 v[26:27], s[14:15], 0, v[14:15]
	global_store_dwordx4 v[20:21], v[22:25], off
	global_store_dwordx2 v[26:27], v[16:17], off
	v_mul_f32_e32 v16, v23, v23
	v_mul_f32_e32 v17, v25, v25
	v_fmac_f32_e32 v16, v22, v22
	v_fmac_f32_e32 v17, v24, v24
	v_add_f32_e32 v26, v16, v17
	s_waitcnt vmcnt(22)
	v_mov_b64_e32 v[22:23], v[228:229]
	v_mov_b64_e32 v[24:25], v[230:231]
	v_pk_fma_f32 v[12:13], v[12:13], 0.5, v[24:25] op_sel_hi:[1,0,1]
	v_pk_fma_f32 v[10:11], v[10:11], 0.5, v[22:23] op_sel_hi:[1,0,1]
	global_store_dwordx4 v[20:21], v[10:13], off offset:64
	v_cvt_pk_bf16_f32 v16, v10, v11
	v_or_b32_e32 v22, 32, v14
	v_mul_f32_e32 v11, v11, v11
	v_mov_b32_e32 v23, v15
	v_fmac_f32_e32 v11, v10, v10
	v_mul_f32_e32 v10, v13, v13
	v_cvt_pk_bf16_f32 v17, v12, v13
	v_lshl_add_u64 v[22:23], s[14:15], 0, v[22:23]
	v_fmac_f32_e32 v10, v12, v12
	global_store_dwordx2 v[22:23], v[16:17], off
	v_add_f32_e32 v10, v11, v10
	v_add_f32_e32 v16, v26, v10
	s_waitcnt vmcnt(23)
	v_mov_b64_e32 v[10:11], v[232:233]
	v_mov_b64_e32 v[12:13], v[234:235]
	v_pk_fma_f32 v[8:9], v[8:9], 0.5, v[12:13] op_sel_hi:[1,0,1]
	v_pk_fma_f32 v[6:7], v[6:7], 0.5, v[10:11] op_sel_hi:[1,0,1]
	global_store_dwordx4 v[20:21], v[6:9], off offset:512
	v_cvt_pk_bf16_f32 v10, v6, v7
	v_or_b32_e32 v12, 0x100, v14
	v_mul_f32_e32 v7, v7, v7
	v_mov_b32_e32 v13, v15
	v_fmac_f32_e32 v7, v6, v6
	v_mul_f32_e32 v6, v9, v9
	v_cvt_pk_bf16_f32 v11, v8, v9
	v_lshl_add_u64 v[12:13], s[14:15], 0, v[12:13]
	v_fmac_f32_e32 v6, v8, v8
	global_store_dwordx2 v[12:13], v[10:11], off
	v_add_f32_e32 v6, v7, v6
	v_add_f32_e32 v10, v16, v6
	v_or_b32_e32 v14, 0x120, v14
	s_waitcnt vmcnt(24)
	v_mov_b64_e32 v[6:7], v[236:237]
	v_mov_b64_e32 v[8:9], v[238:239]
	v_pk_fma_f32 v[4:5], v[4:5], 0.5, v[8:9] op_sel_hi:[1,0,1]
	v_pk_fma_f32 v[2:3], v[2:3], 0.5, v[6:7] op_sel_hi:[1,0,1]
	global_store_dwordx4 v[20:21], v[2:5], off offset:576
	v_cvt_pk_bf16_f32 v6, v2, v3
	v_cvt_pk_bf16_f32 v7, v4, v5
	v_mul_f32_e32 v3, v3, v3
	v_fmac_f32_e32 v3, v2, v2
	v_mul_f32_e32 v2, v5, v5
	v_fmac_f32_e32 v2, v4, v4
	v_add_f32_e32 v2, v3, v2
	v_add_f32_e32 v2, v10, v2
	ds_bpermute_b32 v3, v162, v2
	v_lshl_add_u64 v[8:9], s[14:15], 0, v[14:15]
	global_store_dwordx2 v[8:9], v[6:7], off
	s_waitcnt lgkmcnt(0)
	v_add_f32_e32 v2, v2, v3
	ds_bpermute_b32 v3, v160, v2
	s_and_saveexec_b64 s[22:23], s[8:9]
	s_cbranch_execz .LBB0_329
	v_lshlrev_b64 v[4:5], 6, v[18:19]
	v_lshl_add_u64 v[4:5], s[66:67], 0, v[4:5]
	v_lshl_add_u64 v[4:5], s[20:21], 2, v[4:5]
	s_lshl_b32 s68, s39, 2
	v_lshl_add_u64 v[4:5], v[4:5], 0, s[68:69]
	s_waitcnt lgkmcnt(0)
	v_add_f32_e32 v2, v2, v3
	global_store_dword v[4:5], v2, off

.LBB0_1521:
	v_and_b32_e32 v140, 64, v197
	v_xor_b32_e32 v139, 16, v197
	v_add_u32_e32 v140, 64, v140
	v_cmp_lt_i32_e32 vcc, v139, v140
	v_lshl_add_u32 v138, s48, 8, v142
	v_lshl_or_b32 v136, s47, 8, v144
	v_cndmask_b32_e32 v139, v197, v139, vcc
	v_lshlrev_b32_e32 v162, 2, v139
	v_xor_b32_e32 v139, 32, v197
	v_cmp_lt_i32_e32 vcc, v139, v140
	v_ashrrev_i32_e32 v137, 31, v136
	s_lshl_b32 s24, s47, 2
	v_cndmask_b32_e32 v139, v197, v139, vcc
	v_lshlrev_b32_e32 v160, 2, v139
	v_ashrrev_i32_e32 v139, 31, v138
	v_lshlrev_b64 v[140:141], 10, v[138:139]
	v_lshl_add_u64 v[168:169], v[140:141], 0, v[136:137]
	v_lshl_add_u64 v[140:141], v[168:169], 2, s[4:5]
	v_mov_b64_e32 v[204:205], v[140:141]
	global_load_dwordx4 v[208:211], v[204:205], off
	global_load_dwordx4 v[212:215], v[204:205], off offset:64
	global_load_dwordx4 v[216:219], v[204:205], off offset:512
	global_load_dwordx4 v[220:223], v[204:205], off offset:576
	s_mov_b64 s[26:27], 0x10000
	v_lshl_add_u64 v[206:207], v[204:205], 0, s[26:27]
	global_load_dwordx4 v[224:227], v[206:207], off
	global_load_dwordx4 v[228:231], v[206:207], off offset:64
	global_load_dwordx4 v[232:235], v[206:207], off offset:512
	global_load_dwordx4 v[236:239], v[206:207], off offset:576
	s_mov_b64 s[26:27], 0x20000
	v_lshl_add_u64 v[206:207], v[204:205], 0, s[26:27]
	global_load_dwordx4 v[170:173], v[206:207], off
	global_load_dwordx4 v[174:177], v[206:207], off offset:64
	global_load_dwordx4 v[186:189], v[206:207], off offset:512
	global_load_dwordx4 v[240:243], v[206:207], off offset:576
	s_ashr_i32 s25, s24, 31
	s_waitcnt vmcnt(11)
	v_mov_b64_e32 v[164:165], v[208:209]
	v_mov_b64_e32 v[166:167], v[210:211]
	v_pk_add_f32 v[166:167], v[128:129], v[166:167]
	v_pk_add_f32 v[164:165], v[126:127], v[164:165]
	v_lshlrev_b64 v[126:127], 1, v[168:169]
	v_cvt_pk_bf16_f32 v128, v164, v165
	v_cvt_pk_bf16_f32 v129, v166, v167
	v_lshl_add_u64 v[168:169], s[12:13], 0, v[126:127]
	global_store_dwordx4 v[140:141], v[164:167], off
	global_store_dwordx2 v[168:169], v[128:129], off
	v_mul_f32_e32 v128, v165, v165
	v_mul_f32_e32 v129, v167, v167
	v_fmac_f32_e32 v128, v164, v164
	v_fmac_f32_e32 v129, v166, v166
	v_add_f32_e32 v163, v128, v129
	s_waitcnt vmcnt(12)
	v_mov_b64_e32 v[164:165], v[212:213]
	v_mov_b64_e32 v[166:167], v[214:215]
	v_pk_add_f32 v[124:125], v[124:125], v[166:167]
	v_pk_add_f32 v[122:123], v[122:123], v[164:165]
	global_store_dwordx4 v[140:141], v[122:125], off offset:64
	v_cvt_pk_bf16_f32 v128, v122, v123
	v_or_b32_e32 v164, 32, v126
	v_mul_f32_e32 v123, v123, v123
	v_mov_b32_e32 v165, v127
	v_fmac_f32_e32 v123, v122, v122
	v_mul_f32_e32 v122, v125, v125
	v_cvt_pk_bf16_f32 v129, v124, v125
	v_lshl_add_u64 v[164:165], s[12:13], 0, v[164:165]
	v_fmac_f32_e32 v122, v124, v124
	global_store_dwordx2 v[164:165], v[128:129], off
	v_add_f32_e32 v122, v123, v122
	v_add_f32_e32 v128, v163, v122
	s_waitcnt vmcnt(13)
	v_mov_b64_e32 v[122:123], v[216:217]
	v_mov_b64_e32 v[124:125], v[218:219]
	v_pk_add_f32 v[120:121], v[120:121], v[124:125]
	v_pk_add_f32 v[118:119], v[118:119], v[122:123]
	global_store_dwordx4 v[140:141], v[118:121], off offset:512
	v_cvt_pk_bf16_f32 v122, v118, v119
	v_or_b32_e32 v124, 0x100, v126
	v_mul_f32_e32 v119, v119, v119
	v_mov_b32_e32 v125, v127
	v_fmac_f32_e32 v119, v118, v118
	v_mul_f32_e32 v118, v121, v121
	v_cvt_pk_bf16_f32 v123, v120, v121
	v_lshl_add_u64 v[124:125], s[12:13], 0, v[124:125]
	v_fmac_f32_e32 v118, v120, v120
	global_store_dwordx2 v[124:125], v[122:123], off
	v_add_f32_e32 v118, v119, v118
	v_add_f32_e32 v122, v128, v118
	v_or_b32_e32 v126, 0x120, v126
	s_waitcnt vmcnt(14)
	v_mov_b64_e32 v[118:119], v[220:221]
	v_mov_b64_e32 v[120:121], v[222:223]
	v_pk_add_f32 v[116:117], v[116:117], v[120:121]
	v_pk_add_f32 v[114:115], v[114:115], v[118:119]
	global_store_dwordx4 v[140:141], v[114:117], off offset:576
	v_cvt_pk_bf16_f32 v118, v114, v115
	v_cvt_pk_bf16_f32 v119, v116, v117
	v_mul_f32_e32 v115, v115, v115
	v_fmac_f32_e32 v115, v114, v114
	v_mul_f32_e32 v114, v117, v117
	v_fmac_f32_e32 v114, v116, v116
	v_add_f32_e32 v114, v115, v114
	v_add_f32_e32 v114, v122, v114
	ds_bpermute_b32 v115, v162, v114
	v_lshl_add_u64 v[120:121], s[12:13], 0, v[126:127]
	global_store_dwordx2 v[120:121], v[118:119], off
	s_waitcnt lgkmcnt(0)
	v_add_f32_e32 v114, v114, v115
	ds_bpermute_b32 v115, v160, v114
	s_and_saveexec_b64 s[26:27], s[8:9]
	s_cbranch_execz .LBB0_1523
	v_lshlrev_b64 v[116:117], 6, v[138:139]
	v_lshl_add_u64 v[116:117], s[66:67], 0, v[116:117]
	v_lshl_add_u64 v[116:117], s[24:25], 2, v[116:117]
	s_lshl_b32 s68, s43, 2
	v_lshl_add_u64 v[116:117], v[116:117], 0, s[68:69]
	s_waitcnt lgkmcnt(0)
	v_add_f32_e32 v114, v114, v115
	global_store_dword v[116:117], v114, off
.LBB0_1523:
	s_or_b64 exec, exec, s[26:27]
	v_or_b32_e32 v114, 16, v138
	s_waitcnt lgkmcnt(0)
	v_ashrrev_i32_e32 v115, 31, v114
	v_lshlrev_b64 v[116:117], 10, v[114:115]
	v_lshl_add_u64 v[122:123], v[116:117], 0, v[136:137]
	v_lshl_add_u64 v[116:117], v[122:123], 2, s[4:5]
	s_mov_b64 s[26:27], 0x30000
	v_lshl_add_u64 v[206:207], v[204:205], 0, s[26:27]
	global_load_dwordx4 v[208:211], v[206:207], off
	global_load_dwordx4 v[212:215], v[206:207], off offset:64
	global_load_dwordx4 v[216:219], v[206:207], off offset:512
	global_load_dwordx4 v[220:223], v[206:207], off offset:576
	s_waitcnt vmcnt(20)
	v_mov_b64_e32 v[118:119], v[224:225]
	v_mov_b64_e32 v[120:121], v[226:227]
	v_pk_add_f32 v[120:121], v[112:113], v[120:121]
	v_pk_add_f32 v[118:119], v[110:111], v[118:119]
	v_lshlrev_b64 v[110:111], 1, v[122:123]
	v_cvt_pk_bf16_f32 v112, v118, v119
	v_cvt_pk_bf16_f32 v113, v120, v121
	v_lshl_add_u64 v[122:123], s[12:13], 0, v[110:111]
	global_store_dwordx4 v[116:117], v[118:121], off
	global_store_dwordx2 v[122:123], v[112:113], off
	v_mul_f32_e32 v112, v119, v119
	v_mul_f32_e32 v113, v121, v121
	v_fmac_f32_e32 v112, v118, v118
	v_fmac_f32_e32 v113, v120, v120
	v_add_f32_e32 v122, v112, v113
	s_waitcnt vmcnt(21)
	v_mov_b64_e32 v[118:119], v[228:229]
	v_mov_b64_e32 v[120:121], v[230:231]
	v_pk_add_f32 v[108:109], v[108:109], v[120:121]
	v_pk_add_f32 v[106:107], v[106:107], v[118:119]
	global_store_dwordx4 v[116:117], v[106:109], off offset:64
	v_cvt_pk_bf16_f32 v112, v106, v107
	v_or_b32_e32 v118, 32, v110
	v_mul_f32_e32 v107, v107, v107
	v_mov_b32_e32 v119, v111
	v_fmac_f32_e32 v107, v106, v106
	v_mul_f32_e32 v106, v109, v109
	v_cvt_pk_bf16_f32 v113, v108, v109
	v_lshl_add_u64 v[118:119], s[12:13], 0, v[118:119]
	v_fmac_f32_e32 v106, v108, v108
	global_store_dwordx2 v[118:119], v[112:113], off
	v_add_f32_e32 v106, v107, v106
	v_add_f32_e32 v112, v122, v106
	s_waitcnt vmcnt(22)
	v_mov_b64_e32 v[106:107], v[232:233]
	v_mov_b64_e32 v[108:109], v[234:235]
	v_pk_add_f32 v[104:105], v[104:105], v[108:109]
	v_pk_add_f32 v[102:103], v[102:103], v[106:107]
	global_store_dwordx4 v[116:117], v[102:105], off offset:512
	v_cvt_pk_bf16_f32 v106, v102, v103
	v_or_b32_e32 v108, 0x100, v110
	v_mul_f32_e32 v103, v103, v103
	v_mov_b32_e32 v109, v111
	v_fmac_f32_e32 v103, v102, v102
	v_mul_f32_e32 v102, v105, v105
	v_cvt_pk_bf16_f32 v107, v104, v105
	v_lshl_add_u64 v[108:109], s[12:13], 0, v[108:109]
	v_fmac_f32_e32 v102, v104, v104
	global_store_dwordx2 v[108:109], v[106:107], off
	v_add_f32_e32 v102, v103, v102
	v_add_f32_e32 v106, v112, v102
	v_or_b32_e32 v110, 0x120, v110
	s_waitcnt vmcnt(23)
	v_mov_b64_e32 v[102:103], v[236:237]
	v_mov_b64_e32 v[104:105], v[238:239]
	v_pk_add_f32 v[100:101], v[100:101], v[104:105]
	v_pk_add_f32 v[98:99], v[98:99], v[102:103]
	global_store_dwordx4 v[116:117], v[98:101], off offset:576
	v_cvt_pk_bf16_f32 v102, v98, v99
	v_cvt_pk_bf16_f32 v103, v100, v101
	v_mul_f32_e32 v99, v99, v99
	v_fmac_f32_e32 v99, v98, v98
	v_mul_f32_e32 v98, v101, v101
	v_fmac_f32_e32 v98, v100, v100
	v_add_f32_e32 v98, v99, v98
	v_add_f32_e32 v98, v106, v98
	ds_bpermute_b32 v99, v162, v98
	v_lshl_add_u64 v[104:105], s[12:13], 0, v[110:111]
	global_store_dwordx2 v[104:105], v[102:103], off
	s_waitcnt lgkmcnt(0)
	v_add_f32_e32 v98, v98, v99
	ds_bpermute_b32 v99, v160, v98
	s_and_saveexec_b64 s[26:27], s[8:9]
	s_cbranch_execz .LBB0_1525
	v_lshlrev_b64 v[100:101], 6, v[114:115]
	v_lshl_add_u64 v[100:101], s[66:67], 0, v[100:101]
	v_lshl_add_u64 v[100:101], s[24:25], 2, v[100:101]
	s_lshl_b32 s68, s43, 2
	v_lshl_add_u64 v[100:101], v[100:101], 0, s[68:69]
	s_waitcnt lgkmcnt(0)
	v_add_f32_e32 v98, v98, v99
	global_store_dword v[100:101], v98, off
.LBB0_1525:
	s_or_b64 exec, exec, s[26:27]
	v_or_b32_e32 v98, 32, v138
	s_waitcnt lgkmcnt(0)
	v_ashrrev_i32_e32 v99, 31, v98
	v_lshlrev_b64 v[100:101], 10, v[98:99]
	v_lshl_add_u64 v[106:107], v[100:101], 0, v[136:137]
	v_lshl_add_u64 v[100:101], v[106:107], 2, s[4:5]
	s_mov_b64 s[26:27], 0x80000
	v_lshl_add_u64 v[206:207], v[204:205], 0, s[26:27]
	global_load_dwordx4 v[224:227], v[206:207], off
	global_load_dwordx4 v[228:231], v[206:207], off offset:64
	global_load_dwordx4 v[232:235], v[206:207], off offset:512
	global_load_dwordx4 v[236:239], v[206:207], off offset:576
	s_waitcnt vmcnt(29)
	v_mov_b64_e32 v[102:103], v[170:171]
	v_mov_b64_e32 v[104:105], v[172:173]
	v_pk_add_f32 v[104:105], v[96:97], v[104:105]
	v_pk_add_f32 v[102:103], v[94:95], v[102:103]
	v_lshlrev_b64 v[94:95], 1, v[106:107]
	v_cvt_pk_bf16_f32 v96, v102, v103
	v_cvt_pk_bf16_f32 v97, v104, v105
	v_lshl_add_u64 v[106:107], s[12:13], 0, v[94:95]
	global_store_dwordx4 v[100:101], v[102:105], off
	global_store_dwordx2 v[106:107], v[96:97], off
	v_mul_f32_e32 v96, v103, v103
	v_mul_f32_e32 v97, v105, v105
	v_fmac_f32_e32 v96, v102, v102
	v_fmac_f32_e32 v97, v104, v104
	v_add_f32_e32 v106, v96, v97
	s_waitcnt vmcnt(30)
	v_mov_b64_e32 v[102:103], v[174:175]
	v_mov_b64_e32 v[104:105], v[176:177]
	v_pk_add_f32 v[92:93], v[92:93], v[104:105]
	v_pk_add_f32 v[90:91], v[90:91], v[102:103]
	global_store_dwordx4 v[100:101], v[90:93], off offset:64
	v_cvt_pk_bf16_f32 v96, v90, v91
	v_or_b32_e32 v102, 32, v94
	v_mul_f32_e32 v91, v91, v91
	v_mov_b32_e32 v103, v95
	v_fmac_f32_e32 v91, v90, v90
	v_mul_f32_e32 v90, v93, v93
	v_cvt_pk_bf16_f32 v97, v92, v93
	v_lshl_add_u64 v[102:103], s[12:13], 0, v[102:103]
	v_fmac_f32_e32 v90, v92, v92
	global_store_dwordx2 v[102:103], v[96:97], off
	v_add_f32_e32 v90, v91, v90
	v_add_f32_e32 v96, v106, v90
	s_waitcnt vmcnt(31)
	v_mov_b64_e32 v[90:91], v[186:187]
	v_mov_b64_e32 v[92:93], v[188:189]
	v_pk_add_f32 v[88:89], v[88:89], v[92:93]
	v_pk_add_f32 v[86:87], v[86:87], v[90:91]
	global_store_dwordx4 v[100:101], v[86:89], off offset:512
	v_cvt_pk_bf16_f32 v90, v86, v87
	v_or_b32_e32 v92, 0x100, v94
	v_mul_f32_e32 v87, v87, v87
	v_mov_b32_e32 v93, v95
	v_fmac_f32_e32 v87, v86, v86
	v_mul_f32_e32 v86, v89, v89
	v_cvt_pk_bf16_f32 v91, v88, v89
	v_lshl_add_u64 v[92:93], s[12:13], 0, v[92:93]
	v_fmac_f32_e32 v86, v88, v88
	global_store_dwordx2 v[92:93], v[90:91], off
	v_add_f32_e32 v86, v87, v86
	v_add_f32_e32 v90, v96, v86
	v_or_b32_e32 v94, 0x120, v94
	s_waitcnt vmcnt(32)
	v_mov_b64_e32 v[86:87], v[240:241]
	v_mov_b64_e32 v[88:89], v[242:243]
	v_pk_add_f32 v[84:85], v[84:85], v[88:89]
	v_pk_add_f32 v[82:83], v[82:83], v[86:87]
	global_store_dwordx4 v[100:101], v[82:85], off offset:576
	v_cvt_pk_bf16_f32 v86, v82, v83
	v_cvt_pk_bf16_f32 v87, v84, v85
	v_mul_f32_e32 v83, v83, v83
	v_fmac_f32_e32 v83, v82, v82
	v_mul_f32_e32 v82, v85, v85
	v_fmac_f32_e32 v82, v84, v84
	v_add_f32_e32 v82, v83, v82
	v_add_f32_e32 v82, v90, v82
	ds_bpermute_b32 v83, v162, v82
	v_lshl_add_u64 v[88:89], s[12:13], 0, v[94:95]
	global_store_dwordx2 v[88:89], v[86:87], off
	s_waitcnt lgkmcnt(0)
	v_add_f32_e32 v82, v82, v83
	ds_bpermute_b32 v83, v160, v82
	s_and_saveexec_b64 s[26:27], s[8:9]
	s_cbranch_execz .LBB0_1527
	v_lshlrev_b64 v[84:85], 6, v[98:99]
	v_lshl_add_u64 v[84:85], s[66:67], 0, v[84:85]
	v_lshl_add_u64 v[84:85], s[24:25], 2, v[84:85]
	s_lshl_b32 s68, s43, 2
	v_lshl_add_u64 v[84:85], v[84:85], 0, s[68:69]
	s_waitcnt lgkmcnt(0)
	v_add_f32_e32 v82, v82, v83
	global_store_dword v[84:85], v82, off
.LBB0_1527:
	s_or_b64 exec, exec, s[26:27]
	v_or_b32_e32 v82, 48, v138
	s_waitcnt lgkmcnt(0)
	v_ashrrev_i32_e32 v83, 31, v82
	v_lshlrev_b64 v[84:85], 10, v[82:83]
	v_lshl_add_u64 v[90:91], v[84:85], 0, v[136:137]
	v_lshl_add_u64 v[84:85], v[90:91], 2, s[4:5]
	s_mov_b64 s[26:27], 0x90000
	v_lshl_add_u64 v[206:207], v[204:205], 0, s[26:27]
	global_load_dwordx4 v[170:173], v[206:207], off
	global_load_dwordx4 v[174:177], v[206:207], off offset:64
	global_load_dwordx4 v[186:189], v[206:207], off offset:512
	global_load_dwordx4 v[240:243], v[206:207], off offset:576
	s_waitcnt vmcnt(29)
	v_mov_b64_e32 v[86:87], v[208:209]
	v_mov_b64_e32 v[88:89], v[210:211]
	v_pk_add_f32 v[88:89], v[80:81], v[88:89]
	v_pk_add_f32 v[86:87], v[78:79], v[86:87]
	v_lshlrev_b64 v[78:79], 1, v[90:91]
	v_cvt_pk_bf16_f32 v80, v86, v87
	v_cvt_pk_bf16_f32 v81, v88, v89
	v_lshl_add_u64 v[90:91], s[12:13], 0, v[78:79]
	global_store_dwordx4 v[84:85], v[86:89], off
	global_store_dwordx2 v[90:91], v[80:81], off
	v_mul_f32_e32 v80, v87, v87
	v_mul_f32_e32 v81, v89, v89
	v_fmac_f32_e32 v80, v86, v86
	v_fmac_f32_e32 v81, v88, v88
	v_add_f32_e32 v90, v80, v81
	s_waitcnt vmcnt(30)
	v_mov_b64_e32 v[86:87], v[212:213]
	v_mov_b64_e32 v[88:89], v[214:215]
	v_pk_add_f32 v[76:77], v[76:77], v[88:89]
	v_pk_add_f32 v[74:75], v[74:75], v[86:87]
	global_store_dwordx4 v[84:85], v[74:77], off offset:64
	v_cvt_pk_bf16_f32 v80, v74, v75
	v_or_b32_e32 v86, 32, v78
	v_mul_f32_e32 v75, v75, v75
	v_mov_b32_e32 v87, v79
	v_fmac_f32_e32 v75, v74, v74
	v_mul_f32_e32 v74, v77, v77
	v_cvt_pk_bf16_f32 v81, v76, v77
	v_lshl_add_u64 v[86:87], s[12:13], 0, v[86:87]
	v_fmac_f32_e32 v74, v76, v76
	global_store_dwordx2 v[86:87], v[80:81], off
	v_add_f32_e32 v74, v75, v74
	v_add_f32_e32 v80, v90, v74
	s_waitcnt vmcnt(31)
	v_mov_b64_e32 v[74:75], v[216:217]
	v_mov_b64_e32 v[76:77], v[218:219]
	v_pk_add_f32 v[72:73], v[72:73], v[76:77]
	v_pk_add_f32 v[70:71], v[70:71], v[74:75]
	global_store_dwordx4 v[84:85], v[70:73], off offset:512
	v_cvt_pk_bf16_f32 v74, v70, v71
	v_or_b32_e32 v76, 0x100, v78
	v_mul_f32_e32 v71, v71, v71
	v_mov_b32_e32 v77, v79
	v_fmac_f32_e32 v71, v70, v70
	v_mul_f32_e32 v70, v73, v73
	v_cvt_pk_bf16_f32 v75, v72, v73
	v_lshl_add_u64 v[76:77], s[12:13], 0, v[76:77]
	v_fmac_f32_e32 v70, v72, v72
	global_store_dwordx2 v[76:77], v[74:75], off
	v_add_f32_e32 v70, v71, v70
	v_add_f32_e32 v74, v80, v70
	v_or_b32_e32 v78, 0x120, v78
	s_waitcnt vmcnt(32)
	v_mov_b64_e32 v[70:71], v[220:221]
	v_mov_b64_e32 v[72:73], v[222:223]
	v_pk_add_f32 v[68:69], v[68:69], v[72:73]
	v_pk_add_f32 v[66:67], v[66:67], v[70:71]
	global_store_dwordx4 v[84:85], v[66:69], off offset:576
	v_cvt_pk_bf16_f32 v70, v66, v67
	v_cvt_pk_bf16_f32 v71, v68, v69
	v_mul_f32_e32 v67, v67, v67
	v_fmac_f32_e32 v67, v66, v66
	v_mul_f32_e32 v66, v69, v69
	v_fmac_f32_e32 v66, v68, v68
	v_add_f32_e32 v66, v67, v66
	v_add_f32_e32 v66, v74, v66
	ds_bpermute_b32 v67, v162, v66
	v_lshl_add_u64 v[72:73], s[12:13], 0, v[78:79]
	global_store_dwordx2 v[72:73], v[70:71], off
	s_waitcnt lgkmcnt(0)
	v_add_f32_e32 v66, v66, v67
	ds_bpermute_b32 v67, v160, v66
	s_and_saveexec_b64 s[26:27], s[8:9]
	s_cbranch_execz .LBB0_1529
	v_lshlrev_b64 v[68:69], 6, v[82:83]
	v_lshl_add_u64 v[68:69], s[66:67], 0, v[68:69]
	v_lshl_add_u64 v[68:69], s[24:25], 2, v[68:69]
	s_lshl_b32 s68, s43, 2
	v_lshl_add_u64 v[68:69], v[68:69], 0, s[68:69]
	s_waitcnt lgkmcnt(0)
	v_add_f32_e32 v66, v66, v67
	global_store_dword v[68:69], v66, off
.LBB0_1529:
	s_or_b64 exec, exec, s[26:27]
	v_add_u32_e32 v66, 0x80, v138
	s_waitcnt lgkmcnt(0)
	v_ashrrev_i32_e32 v67, 31, v66
	v_lshlrev_b64 v[68:69], 10, v[66:67]
	v_lshl_add_u64 v[74:75], v[68:69], 0, v[136:137]
	v_lshl_add_u64 v[68:69], v[74:75], 2, s[4:5]
	s_mov_b64 s[26:27], 0xa0000
	v_lshl_add_u64 v[206:207], v[204:205], 0, s[26:27]
	global_load_dwordx4 v[208:211], v[206:207], off
	global_load_dwordx4 v[212:215], v[206:207], off offset:64
	global_load_dwordx4 v[216:219], v[206:207], off offset:512
	global_load_dwordx4 v[220:223], v[206:207], off offset:576
	s_waitcnt vmcnt(29)
	v_mov_b64_e32 v[70:71], v[224:225]
	v_mov_b64_e32 v[72:73], v[226:227]
	v_pk_add_f32 v[72:73], v[64:65], v[72:73]
	v_pk_add_f32 v[70:71], v[62:63], v[70:71]
	v_lshlrev_b64 v[62:63], 1, v[74:75]
	v_cvt_pk_bf16_f32 v64, v70, v71
	v_cvt_pk_bf16_f32 v65, v72, v73
	v_lshl_add_u64 v[74:75], s[12:13], 0, v[62:63]
	global_store_dwordx4 v[68:69], v[70:73], off
	global_store_dwordx2 v[74:75], v[64:65], off
	v_mul_f32_e32 v64, v71, v71
	v_mul_f32_e32 v65, v73, v73
	v_fmac_f32_e32 v64, v70, v70
	v_fmac_f32_e32 v65, v72, v72
	v_add_f32_e32 v74, v64, v65
	s_waitcnt vmcnt(30)
	v_mov_b64_e32 v[70:71], v[228:229]
	v_mov_b64_e32 v[72:73], v[230:231]
	v_pk_add_f32 v[60:61], v[60:61], v[72:73]
	v_pk_add_f32 v[58:59], v[58:59], v[70:71]
	global_store_dwordx4 v[68:69], v[58:61], off offset:64
	v_cvt_pk_bf16_f32 v64, v58, v59
	v_or_b32_e32 v70, 32, v62
	v_mul_f32_e32 v59, v59, v59
	v_mov_b32_e32 v71, v63
	v_fmac_f32_e32 v59, v58, v58
	v_mul_f32_e32 v58, v61, v61
	v_cvt_pk_bf16_f32 v65, v60, v61
	v_lshl_add_u64 v[70:71], s[12:13], 0, v[70:71]
	v_fmac_f32_e32 v58, v60, v60
	global_store_dwordx2 v[70:71], v[64:65], off
	v_add_f32_e32 v58, v59, v58
	v_add_f32_e32 v64, v74, v58
	s_waitcnt vmcnt(31)
	v_mov_b64_e32 v[58:59], v[232:233]
	v_mov_b64_e32 v[60:61], v[234:235]
	v_pk_add_f32 v[56:57], v[56:57], v[60:61]
	v_pk_add_f32 v[54:55], v[54:55], v[58:59]
	global_store_dwordx4 v[68:69], v[54:57], off offset:512
	v_cvt_pk_bf16_f32 v58, v54, v55
	v_or_b32_e32 v60, 0x100, v62
	v_mul_f32_e32 v55, v55, v55
	v_mov_b32_e32 v61, v63
	v_fmac_f32_e32 v55, v54, v54
	v_mul_f32_e32 v54, v57, v57
	v_cvt_pk_bf16_f32 v59, v56, v57
	v_lshl_add_u64 v[60:61], s[12:13], 0, v[60:61]
	v_fmac_f32_e32 v54, v56, v56
	global_store_dwordx2 v[60:61], v[58:59], off
	v_add_f32_e32 v54, v55, v54
	v_add_f32_e32 v58, v64, v54
	v_or_b32_e32 v62, 0x120, v62
	s_waitcnt vmcnt(32)
	v_mov_b64_e32 v[54:55], v[236:237]
	v_mov_b64_e32 v[56:57], v[238:239]
	v_pk_add_f32 v[52:53], v[52:53], v[56:57]
	v_pk_add_f32 v[50:51], v[50:51], v[54:55]
	global_store_dwordx4 v[68:69], v[50:53], off offset:576
	v_cvt_pk_bf16_f32 v54, v50, v51
	v_cvt_pk_bf16_f32 v55, v52, v53
	v_mul_f32_e32 v51, v51, v51
	v_fmac_f32_e32 v51, v50, v50
	v_mul_f32_e32 v50, v53, v53
	v_fmac_f32_e32 v50, v52, v52
	v_add_f32_e32 v50, v51, v50
	v_add_f32_e32 v50, v58, v50
	ds_bpermute_b32 v51, v162, v50
	v_lshl_add_u64 v[56:57], s[12:13], 0, v[62:63]
	global_store_dwordx2 v[56:57], v[54:55], off
	s_waitcnt lgkmcnt(0)
	v_add_f32_e32 v50, v50, v51
	ds_bpermute_b32 v51, v160, v50
	s_and_saveexec_b64 s[26:27], s[8:9]
	s_cbranch_execz .LBB0_1531
	v_lshlrev_b64 v[52:53], 6, v[66:67]
	v_lshl_add_u64 v[52:53], s[66:67], 0, v[52:53]
	v_lshl_add_u64 v[52:53], s[24:25], 2, v[52:53]
	s_lshl_b32 s68, s43, 2
	v_lshl_add_u64 v[52:53], v[52:53], 0, s[68:69]
	s_waitcnt lgkmcnt(0)
	v_add_f32_e32 v50, v50, v51
	global_store_dword v[52:53], v50, off
.LBB0_1531:
	s_or_b64 exec, exec, s[26:27]
	v_add_u32_e32 v50, 0x90, v138
	s_waitcnt lgkmcnt(0)
	v_ashrrev_i32_e32 v51, 31, v50
	v_lshlrev_b64 v[52:53], 10, v[50:51]
	v_lshl_add_u64 v[58:59], v[52:53], 0, v[136:137]
	v_lshl_add_u64 v[52:53], v[58:59], 2, s[4:5]
	s_mov_b64 s[26:27], 0xb0000
	v_lshl_add_u64 v[206:207], v[204:205], 0, s[26:27]
	global_load_dwordx4 v[224:227], v[206:207], off
	global_load_dwordx4 v[228:231], v[206:207], off offset:64
	global_load_dwordx4 v[232:235], v[206:207], off offset:512
	global_load_dwordx4 v[236:239], v[206:207], off offset:576
	s_waitcnt vmcnt(29)
	v_mov_b64_e32 v[54:55], v[170:171]
	v_mov_b64_e32 v[56:57], v[172:173]
	v_pk_add_f32 v[56:57], v[48:49], v[56:57]
	v_pk_add_f32 v[54:55], v[46:47], v[54:55]
	v_lshlrev_b64 v[46:47], 1, v[58:59]
	v_cvt_pk_bf16_f32 v48, v54, v55
	v_cvt_pk_bf16_f32 v49, v56, v57
	v_lshl_add_u64 v[58:59], s[12:13], 0, v[46:47]
	global_store_dwordx4 v[52:53], v[54:57], off
	global_store_dwordx2 v[58:59], v[48:49], off
	v_mul_f32_e32 v48, v55, v55
	v_mul_f32_e32 v49, v57, v57
	v_fmac_f32_e32 v48, v54, v54
	v_fmac_f32_e32 v49, v56, v56
	v_add_f32_e32 v58, v48, v49
	s_waitcnt vmcnt(30)
	v_mov_b64_e32 v[54:55], v[174:175]
	v_mov_b64_e32 v[56:57], v[176:177]
	v_pk_add_f32 v[44:45], v[44:45], v[56:57]
	v_pk_add_f32 v[42:43], v[42:43], v[54:55]
	global_store_dwordx4 v[52:53], v[42:45], off offset:64
	v_cvt_pk_bf16_f32 v48, v42, v43
	v_or_b32_e32 v54, 32, v46
	v_mul_f32_e32 v43, v43, v43
	v_mov_b32_e32 v55, v47
	v_fmac_f32_e32 v43, v42, v42
	v_mul_f32_e32 v42, v45, v45
	v_cvt_pk_bf16_f32 v49, v44, v45
	v_lshl_add_u64 v[54:55], s[12:13], 0, v[54:55]
	v_fmac_f32_e32 v42, v44, v44
	global_store_dwordx2 v[54:55], v[48:49], off
	v_add_f32_e32 v42, v43, v42
	v_add_f32_e32 v48, v58, v42
	s_waitcnt vmcnt(31)
	v_mov_b64_e32 v[42:43], v[186:187]
	v_mov_b64_e32 v[44:45], v[188:189]
	v_pk_add_f32 v[40:41], v[40:41], v[44:45]
	v_pk_add_f32 v[38:39], v[38:39], v[42:43]
	global_store_dwordx4 v[52:53], v[38:41], off offset:512
	v_cvt_pk_bf16_f32 v42, v38, v39
	v_or_b32_e32 v44, 0x100, v46
	v_mul_f32_e32 v39, v39, v39
	v_mov_b32_e32 v45, v47
	v_fmac_f32_e32 v39, v38, v38
	v_mul_f32_e32 v38, v41, v41
	v_cvt_pk_bf16_f32 v43, v40, v41
	v_lshl_add_u64 v[44:45], s[12:13], 0, v[44:45]
	v_fmac_f32_e32 v38, v40, v40
	global_store_dwordx2 v[44:45], v[42:43], off
	v_add_f32_e32 v38, v39, v38
	v_add_f32_e32 v42, v48, v38
	v_or_b32_e32 v46, 0x120, v46
	s_waitcnt vmcnt(32)
	v_mov_b64_e32 v[38:39], v[240:241]
	v_mov_b64_e32 v[40:41], v[242:243]
	v_pk_add_f32 v[36:37], v[36:37], v[40:41]
	v_pk_add_f32 v[34:35], v[34:35], v[38:39]
	global_store_dwordx4 v[52:53], v[34:37], off offset:576
	v_cvt_pk_bf16_f32 v38, v34, v35
	v_cvt_pk_bf16_f32 v39, v36, v37
	v_mul_f32_e32 v35, v35, v35
	v_fmac_f32_e32 v35, v34, v34
	v_mul_f32_e32 v34, v37, v37
	v_fmac_f32_e32 v34, v36, v36
	v_add_f32_e32 v34, v35, v34
	v_add_f32_e32 v34, v42, v34
	ds_bpermute_b32 v35, v162, v34
	v_lshl_add_u64 v[40:41], s[12:13], 0, v[46:47]
	global_store_dwordx2 v[40:41], v[38:39], off
	s_waitcnt lgkmcnt(0)
	v_add_f32_e32 v34, v34, v35
	ds_bpermute_b32 v35, v160, v34
	s_and_saveexec_b64 s[26:27], s[8:9]
	s_cbranch_execz .LBB0_1533
	v_lshlrev_b64 v[36:37], 6, v[50:51]
	v_lshl_add_u64 v[36:37], s[66:67], 0, v[36:37]
	v_lshl_add_u64 v[36:37], s[24:25], 2, v[36:37]
	s_lshl_b32 s68, s43, 2
	v_lshl_add_u64 v[36:37], v[36:37], 0, s[68:69]
	s_waitcnt lgkmcnt(0)
	v_add_f32_e32 v34, v34, v35
	global_store_dword v[36:37], v34, off
.LBB0_1533:
	s_or_b64 exec, exec, s[26:27]
	v_add_u32_e32 v34, 0xa0, v138
	s_waitcnt lgkmcnt(0)
	v_ashrrev_i32_e32 v35, 31, v34
	v_lshlrev_b64 v[36:37], 10, v[34:35]
	v_lshl_add_u64 v[42:43], v[36:37], 0, v[136:137]
	v_lshl_add_u64 v[36:37], v[42:43], 2, s[4:5]
	s_waitcnt vmcnt(25)
	v_mov_b64_e32 v[38:39], v[208:209]
	v_mov_b64_e32 v[40:41], v[210:211]
	v_pk_add_f32 v[40:41], v[32:33], v[40:41]
	v_pk_add_f32 v[38:39], v[30:31], v[38:39]
	v_lshlrev_b64 v[30:31], 1, v[42:43]
	v_cvt_pk_bf16_f32 v32, v38, v39
	v_cvt_pk_bf16_f32 v33, v40, v41
	v_lshl_add_u64 v[42:43], s[12:13], 0, v[30:31]
	global_store_dwordx4 v[36:37], v[38:41], off
	global_store_dwordx2 v[42:43], v[32:33], off
	v_mul_f32_e32 v32, v39, v39
	v_mul_f32_e32 v33, v41, v41
	v_fmac_f32_e32 v32, v38, v38
	v_fmac_f32_e32 v33, v40, v40
	v_add_f32_e32 v42, v32, v33
	s_waitcnt vmcnt(26)
	v_mov_b64_e32 v[38:39], v[212:213]
	v_mov_b64_e32 v[40:41], v[214:215]
	v_pk_add_f32 v[28:29], v[28:29], v[40:41]
	v_pk_add_f32 v[26:27], v[26:27], v[38:39]
	global_store_dwordx4 v[36:37], v[26:29], off offset:64
	v_cvt_pk_bf16_f32 v32, v26, v27
	v_or_b32_e32 v38, 32, v30
	v_mul_f32_e32 v27, v27, v27
	v_mov_b32_e32 v39, v31
	v_fmac_f32_e32 v27, v26, v26
	v_mul_f32_e32 v26, v29, v29
	v_cvt_pk_bf16_f32 v33, v28, v29
	v_lshl_add_u64 v[38:39], s[12:13], 0, v[38:39]
	v_fmac_f32_e32 v26, v28, v28
	global_store_dwordx2 v[38:39], v[32:33], off
	v_add_f32_e32 v26, v27, v26
	v_add_f32_e32 v32, v42, v26
	s_waitcnt vmcnt(27)
	v_mov_b64_e32 v[26:27], v[216:217]
	v_mov_b64_e32 v[28:29], v[218:219]
	v_pk_add_f32 v[24:25], v[24:25], v[28:29]
	v_pk_add_f32 v[22:23], v[22:23], v[26:27]
	global_store_dwordx4 v[36:37], v[22:25], off offset:512
	v_cvt_pk_bf16_f32 v26, v22, v23
	v_or_b32_e32 v28, 0x100, v30
	v_mul_f32_e32 v23, v23, v23
	v_mov_b32_e32 v29, v31
	v_fmac_f32_e32 v23, v22, v22
	v_mul_f32_e32 v22, v25, v25
	v_cvt_pk_bf16_f32 v27, v24, v25
	v_lshl_add_u64 v[28:29], s[12:13], 0, v[28:29]
	v_fmac_f32_e32 v22, v24, v24
	global_store_dwordx2 v[28:29], v[26:27], off
	v_add_f32_e32 v22, v23, v22
	v_add_f32_e32 v26, v32, v22
	v_or_b32_e32 v30, 0x120, v30
	s_waitcnt vmcnt(28)
	v_mov_b64_e32 v[22:23], v[220:221]
	v_mov_b64_e32 v[24:25], v[222:223]
	v_pk_add_f32 v[20:21], v[20:21], v[24:25]
	v_pk_add_f32 v[18:19], v[18:19], v[22:23]
	global_store_dwordx4 v[36:37], v[18:21], off offset:576
	v_cvt_pk_bf16_f32 v22, v18, v19
	v_cvt_pk_bf16_f32 v23, v20, v21
	v_mul_f32_e32 v19, v19, v19
	v_fmac_f32_e32 v19, v18, v18
	v_mul_f32_e32 v18, v21, v21
	v_fmac_f32_e32 v18, v20, v20
	v_add_f32_e32 v18, v19, v18
	v_add_f32_e32 v18, v26, v18
	ds_bpermute_b32 v19, v162, v18
	v_lshl_add_u64 v[24:25], s[12:13], 0, v[30:31]
	global_store_dwordx2 v[24:25], v[22:23], off
	s_waitcnt lgkmcnt(0)
	v_add_f32_e32 v18, v18, v19
	ds_bpermute_b32 v19, v160, v18
	s_and_saveexec_b64 s[26:27], s[8:9]
	s_cbranch_execz .LBB0_1535
	v_lshlrev_b64 v[20:21], 6, v[34:35]
	v_lshl_add_u64 v[20:21], s[66:67], 0, v[20:21]
	v_lshl_add_u64 v[20:21], s[24:25], 2, v[20:21]
	s_lshl_b32 s68, s43, 2
	v_lshl_add_u64 v[20:21], v[20:21], 0, s[68:69]
	s_waitcnt lgkmcnt(0)
	v_add_f32_e32 v18, v18, v19
	global_store_dword v[20:21], v18, off
.LBB0_1535:
	s_or_b64 exec, exec, s[26:27]
	v_add_u32_e32 v18, 0xb0, v138
	s_waitcnt lgkmcnt(0)
	v_ashrrev_i32_e32 v19, 31, v18
	v_lshlrev_b64 v[20:21], 10, v[18:19]
	v_lshl_add_u64 v[26:27], v[20:21], 0, v[136:137]
	v_lshl_add_u64 v[20:21], v[26:27], 2, s[4:5]
	s_waitcnt vmcnt(21)
	v_mov_b64_e32 v[22:23], v[224:225]
	v_mov_b64_e32 v[24:25], v[226:227]
	v_pk_add_f32 v[24:25], v[16:17], v[24:25]
	v_pk_add_f32 v[22:23], v[14:15], v[22:23]
	v_lshlrev_b64 v[14:15], 1, v[26:27]
	v_cvt_pk_bf16_f32 v16, v22, v23
	v_cvt_pk_bf16_f32 v17, v24, v25
	v_lshl_add_u64 v[26:27], s[12:13], 0, v[14:15]
	global_store_dwordx4 v[20:21], v[22:25], off
	global_store_dwordx2 v[26:27], v[16:17], off
	v_mul_f32_e32 v16, v23, v23
	v_mul_f32_e32 v17, v25, v25
	v_fmac_f32_e32 v16, v22, v22
	v_fmac_f32_e32 v17, v24, v24
	v_add_f32_e32 v26, v16, v17
	s_waitcnt vmcnt(22)
	v_mov_b64_e32 v[22:23], v[228:229]
	v_mov_b64_e32 v[24:25], v[230:231]
	v_pk_add_f32 v[12:13], v[12:13], v[24:25]
	v_pk_add_f32 v[10:11], v[10:11], v[22:23]
	global_store_dwordx4 v[20:21], v[10:13], off offset:64
	v_cvt_pk_bf16_f32 v16, v10, v11
	v_or_b32_e32 v22, 32, v14
	v_mul_f32_e32 v11, v11, v11
	v_mov_b32_e32 v23, v15
	v_fmac_f32_e32 v11, v10, v10
	v_mul_f32_e32 v10, v13, v13
	v_cvt_pk_bf16_f32 v17, v12, v13
	v_lshl_add_u64 v[22:23], s[12:13], 0, v[22:23]
	v_fmac_f32_e32 v10, v12, v12
	global_store_dwordx2 v[22:23], v[16:17], off
	v_add_f32_e32 v10, v11, v10
	v_add_f32_e32 v16, v26, v10
	s_waitcnt vmcnt(23)
	v_mov_b64_e32 v[10:11], v[232:233]
	v_mov_b64_e32 v[12:13], v[234:235]
	v_pk_add_f32 v[8:9], v[8:9], v[12:13]
	v_pk_add_f32 v[6:7], v[6:7], v[10:11]
	global_store_dwordx4 v[20:21], v[6:9], off offset:512
	v_cvt_pk_bf16_f32 v10, v6, v7
	v_or_b32_e32 v12, 0x100, v14
	v_mul_f32_e32 v7, v7, v7
	v_mov_b32_e32 v13, v15
	v_fmac_f32_e32 v7, v6, v6
	v_mul_f32_e32 v6, v9, v9
	v_cvt_pk_bf16_f32 v11, v8, v9
	v_lshl_add_u64 v[12:13], s[12:13], 0, v[12:13]
	v_fmac_f32_e32 v6, v8, v8
	global_store_dwordx2 v[12:13], v[10:11], off
	v_add_f32_e32 v6, v7, v6
	v_add_f32_e32 v10, v16, v6
	v_or_b32_e32 v14, 0x120, v14
	s_waitcnt vmcnt(24)
	v_mov_b64_e32 v[6:7], v[236:237]
	v_mov_b64_e32 v[8:9], v[238:239]
	v_pk_add_f32 v[4:5], v[4:5], v[8:9]
	v_pk_add_f32 v[2:3], v[2:3], v[6:7]
	global_store_dwordx4 v[20:21], v[2:5], off offset:576
	v_cvt_pk_bf16_f32 v6, v2, v3
	v_cvt_pk_bf16_f32 v7, v4, v5
	v_mul_f32_e32 v3, v3, v3
	v_fmac_f32_e32 v3, v2, v2
	v_mul_f32_e32 v2, v5, v5
	v_fmac_f32_e32 v2, v4, v4
	v_add_f32_e32 v2, v3, v2
	v_add_f32_e32 v2, v10, v2
	ds_bpermute_b32 v3, v162, v2
	v_lshl_add_u64 v[8:9], s[12:13], 0, v[14:15]
	global_store_dwordx2 v[8:9], v[6:7], off
	s_waitcnt lgkmcnt(0)
	v_add_f32_e32 v2, v2, v3
	ds_bpermute_b32 v3, v160, v2
	s_and_saveexec_b64 s[26:27], s[8:9]
	s_cbranch_execz .LBB0_1537
	v_lshlrev_b64 v[4:5], 6, v[18:19]
	v_lshl_add_u64 v[4:5], s[66:67], 0, v[4:5]
	v_lshl_add_u64 v[4:5], s[24:25], 2, v[4:5]
	s_lshl_b32 s68, s43, 2
	v_lshl_add_u64 v[4:5], v[4:5], 0, s[68:69]
	s_waitcnt lgkmcnt(0)
	v_add_f32_e32 v2, v2, v3
	global_store_dword v[4:5], v2, off

.LBB0_1681:
	v_and_b32_e32 v140, 64, v197
	v_xor_b32_e32 v139, 16, v197
	v_add_u32_e32 v140, 64, v140
	v_cmp_lt_i32_e32 vcc, v139, v140
	v_lshl_add_u32 v138, s46, 8, v142
	v_lshl_or_b32 v136, s45, 8, v144
	v_cndmask_b32_e32 v139, v197, v139, vcc
	v_lshlrev_b32_e32 v162, 2, v139
	v_xor_b32_e32 v139, 32, v197
	v_cmp_lt_i32_e32 vcc, v139, v140
	v_ashrrev_i32_e32 v137, 31, v136
	s_lshl_b32 s20, s45, 2
	v_cndmask_b32_e32 v139, v197, v139, vcc
	v_lshlrev_b32_e32 v160, 2, v139
	v_ashrrev_i32_e32 v139, 31, v138
	v_lshlrev_b64 v[140:141], 10, v[138:139]
	v_lshl_add_u64 v[168:169], v[140:141], 0, v[136:137]
	v_lshl_add_u64 v[140:141], v[168:169], 2, s[10:11]
	v_mov_b64_e32 v[204:205], v[140:141]
	global_load_dwordx4 v[208:211], v[204:205], off
	global_load_dwordx4 v[212:215], v[204:205], off offset:64
	global_load_dwordx4 v[216:219], v[204:205], off offset:512
	global_load_dwordx4 v[220:223], v[204:205], off offset:576
	s_mov_b64 s[22:23], 0x10000
	v_lshl_add_u64 v[206:207], v[204:205], 0, s[22:23]
	global_load_dwordx4 v[224:227], v[206:207], off
	global_load_dwordx4 v[228:231], v[206:207], off offset:64
	global_load_dwordx4 v[232:235], v[206:207], off offset:512
	global_load_dwordx4 v[236:239], v[206:207], off offset:576
	s_mov_b64 s[22:23], 0x20000
	v_lshl_add_u64 v[206:207], v[204:205], 0, s[22:23]
	global_load_dwordx4 v[170:173], v[206:207], off
	global_load_dwordx4 v[174:177], v[206:207], off offset:64
	global_load_dwordx4 v[186:189], v[206:207], off offset:512
	global_load_dwordx4 v[240:243], v[206:207], off offset:576
	s_ashr_i32 s21, s20, 31
	s_waitcnt vmcnt(11)
	v_mov_b64_e32 v[164:165], v[208:209]
	v_mov_b64_e32 v[166:167], v[210:211]
	v_pk_fma_f32 v[166:167], v[128:129], 0.5, v[166:167] op_sel_hi:[1,0,1]
	v_pk_fma_f32 v[164:165], v[126:127], 0.5, v[164:165] op_sel_hi:[1,0,1]
	v_lshlrev_b64 v[126:127], 1, v[168:169]
	v_cvt_pk_bf16_f32 v128, v164, v165
	v_cvt_pk_bf16_f32 v129, v166, v167
	v_lshl_add_u64 v[168:169], s[14:15], 0, v[126:127]
	global_store_dwordx4 v[140:141], v[164:167], off
	global_store_dwordx2 v[168:169], v[128:129], off
	v_mul_f32_e32 v128, v165, v165
	v_mul_f32_e32 v129, v167, v167
	v_fmac_f32_e32 v128, v164, v164
	v_fmac_f32_e32 v129, v166, v166
	v_add_f32_e32 v163, v128, v129
	s_waitcnt vmcnt(12)
	v_mov_b64_e32 v[164:165], v[212:213]
	v_mov_b64_e32 v[166:167], v[214:215]
	v_pk_fma_f32 v[124:125], v[124:125], 0.5, v[166:167] op_sel_hi:[1,0,1]
	v_pk_fma_f32 v[122:123], v[122:123], 0.5, v[164:165] op_sel_hi:[1,0,1]
	global_store_dwordx4 v[140:141], v[122:125], off offset:64
	v_cvt_pk_bf16_f32 v128, v122, v123
	v_or_b32_e32 v164, 32, v126
	v_mul_f32_e32 v123, v123, v123
	v_mov_b32_e32 v165, v127
	v_fmac_f32_e32 v123, v122, v122
	v_mul_f32_e32 v122, v125, v125
	v_cvt_pk_bf16_f32 v129, v124, v125
	v_lshl_add_u64 v[164:165], s[14:15], 0, v[164:165]
	v_fmac_f32_e32 v122, v124, v124
	global_store_dwordx2 v[164:165], v[128:129], off
	v_add_f32_e32 v122, v123, v122
	v_add_f32_e32 v128, v163, v122
	s_waitcnt vmcnt(13)
	v_mov_b64_e32 v[122:123], v[216:217]
	v_mov_b64_e32 v[124:125], v[218:219]
	v_pk_fma_f32 v[120:121], v[120:121], 0.5, v[124:125] op_sel_hi:[1,0,1]
	v_pk_fma_f32 v[118:119], v[118:119], 0.5, v[122:123] op_sel_hi:[1,0,1]
	global_store_dwordx4 v[140:141], v[118:121], off offset:512
	v_cvt_pk_bf16_f32 v122, v118, v119
	v_or_b32_e32 v124, 0x100, v126
	v_mul_f32_e32 v119, v119, v119
	v_mov_b32_e32 v125, v127
	v_fmac_f32_e32 v119, v118, v118
	v_mul_f32_e32 v118, v121, v121
	v_cvt_pk_bf16_f32 v123, v120, v121
	v_lshl_add_u64 v[124:125], s[14:15], 0, v[124:125]
	v_fmac_f32_e32 v118, v120, v120
	global_store_dwordx2 v[124:125], v[122:123], off
	v_add_f32_e32 v118, v119, v118
	v_add_f32_e32 v122, v128, v118
	v_or_b32_e32 v126, 0x120, v126
	s_waitcnt vmcnt(14)
	v_mov_b64_e32 v[118:119], v[220:221]
	v_mov_b64_e32 v[120:121], v[222:223]
	v_pk_fma_f32 v[116:117], v[116:117], 0.5, v[120:121] op_sel_hi:[1,0,1]
	v_pk_fma_f32 v[114:115], v[114:115], 0.5, v[118:119] op_sel_hi:[1,0,1]
	global_store_dwordx4 v[140:141], v[114:117], off offset:576
	v_cvt_pk_bf16_f32 v118, v114, v115
	v_cvt_pk_bf16_f32 v119, v116, v117
	v_mul_f32_e32 v115, v115, v115
	v_fmac_f32_e32 v115, v114, v114
	v_mul_f32_e32 v114, v117, v117
	v_fmac_f32_e32 v114, v116, v116
	v_add_f32_e32 v114, v115, v114
	v_add_f32_e32 v114, v122, v114
	ds_bpermute_b32 v115, v162, v114
	v_lshl_add_u64 v[120:121], s[14:15], 0, v[126:127]
	global_store_dwordx2 v[120:121], v[118:119], off
	s_waitcnt lgkmcnt(0)
	v_add_f32_e32 v114, v114, v115
	ds_bpermute_b32 v115, v160, v114
	s_and_saveexec_b64 s[22:23], s[4:5]
	s_cbranch_execz .LBB0_1683
	v_lshlrev_b64 v[116:117], 6, v[138:139]
	v_lshl_add_u64 v[116:117], s[66:67], 0, v[116:117]
	v_lshl_add_u64 v[116:117], s[20:21], 2, v[116:117]
	s_lshl_b32 s68, s39, 2
	v_lshl_add_u64 v[116:117], v[116:117], 0, s[68:69]
	s_waitcnt lgkmcnt(0)
	v_add_f32_e32 v114, v114, v115
	global_store_dword v[116:117], v114, off
.LBB0_1683:
	s_or_b64 exec, exec, s[22:23]
	v_or_b32_e32 v114, 16, v138
	s_waitcnt lgkmcnt(0)
	v_ashrrev_i32_e32 v115, 31, v114
	v_lshlrev_b64 v[116:117], 10, v[114:115]
	v_lshl_add_u64 v[122:123], v[116:117], 0, v[136:137]
	v_lshl_add_u64 v[116:117], v[122:123], 2, s[10:11]
	s_mov_b64 s[22:23], 0x30000
	v_lshl_add_u64 v[206:207], v[204:205], 0, s[22:23]
	global_load_dwordx4 v[208:211], v[206:207], off
	global_load_dwordx4 v[212:215], v[206:207], off offset:64
	global_load_dwordx4 v[216:219], v[206:207], off offset:512
	global_load_dwordx4 v[220:223], v[206:207], off offset:576
	s_waitcnt vmcnt(20)
	v_mov_b64_e32 v[118:119], v[224:225]
	v_mov_b64_e32 v[120:121], v[226:227]
	v_pk_fma_f32 v[120:121], v[112:113], 0.5, v[120:121] op_sel_hi:[1,0,1]
	v_pk_fma_f32 v[118:119], v[110:111], 0.5, v[118:119] op_sel_hi:[1,0,1]
	v_lshlrev_b64 v[110:111], 1, v[122:123]
	v_cvt_pk_bf16_f32 v112, v118, v119
	v_cvt_pk_bf16_f32 v113, v120, v121
	v_lshl_add_u64 v[122:123], s[14:15], 0, v[110:111]
	global_store_dwordx4 v[116:117], v[118:121], off
	global_store_dwordx2 v[122:123], v[112:113], off
	v_mul_f32_e32 v112, v119, v119
	v_mul_f32_e32 v113, v121, v121
	v_fmac_f32_e32 v112, v118, v118
	v_fmac_f32_e32 v113, v120, v120
	v_add_f32_e32 v122, v112, v113
	s_waitcnt vmcnt(21)
	v_mov_b64_e32 v[118:119], v[228:229]
	v_mov_b64_e32 v[120:121], v[230:231]
	v_pk_fma_f32 v[108:109], v[108:109], 0.5, v[120:121] op_sel_hi:[1,0,1]
	v_pk_fma_f32 v[106:107], v[106:107], 0.5, v[118:119] op_sel_hi:[1,0,1]
	global_store_dwordx4 v[116:117], v[106:109], off offset:64
	v_cvt_pk_bf16_f32 v112, v106, v107
	v_or_b32_e32 v118, 32, v110
	v_mul_f32_e32 v107, v107, v107
	v_mov_b32_e32 v119, v111
	v_fmac_f32_e32 v107, v106, v106
	v_mul_f32_e32 v106, v109, v109
	v_cvt_pk_bf16_f32 v113, v108, v109
	v_lshl_add_u64 v[118:119], s[14:15], 0, v[118:119]
	v_fmac_f32_e32 v106, v108, v108
	global_store_dwordx2 v[118:119], v[112:113], off
	v_add_f32_e32 v106, v107, v106
	v_add_f32_e32 v112, v122, v106
	s_waitcnt vmcnt(22)
	v_mov_b64_e32 v[106:107], v[232:233]
	v_mov_b64_e32 v[108:109], v[234:235]
	v_pk_fma_f32 v[104:105], v[104:105], 0.5, v[108:109] op_sel_hi:[1,0,1]
	v_pk_fma_f32 v[102:103], v[102:103], 0.5, v[106:107] op_sel_hi:[1,0,1]
	global_store_dwordx4 v[116:117], v[102:105], off offset:512
	v_cvt_pk_bf16_f32 v106, v102, v103
	v_or_b32_e32 v108, 0x100, v110
	v_mul_f32_e32 v103, v103, v103
	v_mov_b32_e32 v109, v111
	v_fmac_f32_e32 v103, v102, v102
	v_mul_f32_e32 v102, v105, v105
	v_cvt_pk_bf16_f32 v107, v104, v105
	v_lshl_add_u64 v[108:109], s[14:15], 0, v[108:109]
	v_fmac_f32_e32 v102, v104, v104
	global_store_dwordx2 v[108:109], v[106:107], off
	v_add_f32_e32 v102, v103, v102
	v_add_f32_e32 v106, v112, v102
	v_or_b32_e32 v110, 0x120, v110
	s_waitcnt vmcnt(23)
	v_mov_b64_e32 v[102:103], v[236:237]
	v_mov_b64_e32 v[104:105], v[238:239]
	v_pk_fma_f32 v[100:101], v[100:101], 0.5, v[104:105] op_sel_hi:[1,0,1]
	v_pk_fma_f32 v[98:99], v[98:99], 0.5, v[102:103] op_sel_hi:[1,0,1]
	global_store_dwordx4 v[116:117], v[98:101], off offset:576
	v_cvt_pk_bf16_f32 v102, v98, v99
	v_cvt_pk_bf16_f32 v103, v100, v101
	v_mul_f32_e32 v99, v99, v99
	v_fmac_f32_e32 v99, v98, v98
	v_mul_f32_e32 v98, v101, v101
	v_fmac_f32_e32 v98, v100, v100
	v_add_f32_e32 v98, v99, v98
	v_add_f32_e32 v98, v106, v98
	ds_bpermute_b32 v99, v162, v98
	v_lshl_add_u64 v[104:105], s[14:15], 0, v[110:111]
	global_store_dwordx2 v[104:105], v[102:103], off
	s_waitcnt lgkmcnt(0)
	v_add_f32_e32 v98, v98, v99
	ds_bpermute_b32 v99, v160, v98
	s_and_saveexec_b64 s[22:23], s[4:5]
	s_cbranch_execz .LBB0_1685
	v_lshlrev_b64 v[100:101], 6, v[114:115]
	v_lshl_add_u64 v[100:101], s[66:67], 0, v[100:101]
	v_lshl_add_u64 v[100:101], s[20:21], 2, v[100:101]
	s_lshl_b32 s68, s39, 2
	v_lshl_add_u64 v[100:101], v[100:101], 0, s[68:69]
	s_waitcnt lgkmcnt(0)
	v_add_f32_e32 v98, v98, v99
	global_store_dword v[100:101], v98, off
.LBB0_1685:
	s_or_b64 exec, exec, s[22:23]
	v_or_b32_e32 v98, 32, v138
	s_waitcnt lgkmcnt(0)
	v_ashrrev_i32_e32 v99, 31, v98
	v_lshlrev_b64 v[100:101], 10, v[98:99]
	v_lshl_add_u64 v[106:107], v[100:101], 0, v[136:137]
	v_lshl_add_u64 v[100:101], v[106:107], 2, s[10:11]
	s_mov_b64 s[22:23], 0x80000
	v_lshl_add_u64 v[206:207], v[204:205], 0, s[22:23]
	global_load_dwordx4 v[224:227], v[206:207], off
	global_load_dwordx4 v[228:231], v[206:207], off offset:64
	global_load_dwordx4 v[232:235], v[206:207], off offset:512
	global_load_dwordx4 v[236:239], v[206:207], off offset:576
	s_waitcnt vmcnt(29)
	v_mov_b64_e32 v[102:103], v[170:171]
	v_mov_b64_e32 v[104:105], v[172:173]
	v_pk_fma_f32 v[104:105], v[96:97], 0.5, v[104:105] op_sel_hi:[1,0,1]
	v_pk_fma_f32 v[102:103], v[94:95], 0.5, v[102:103] op_sel_hi:[1,0,1]
	v_lshlrev_b64 v[94:95], 1, v[106:107]
	v_cvt_pk_bf16_f32 v96, v102, v103
	v_cvt_pk_bf16_f32 v97, v104, v105
	v_lshl_add_u64 v[106:107], s[14:15], 0, v[94:95]
	global_store_dwordx4 v[100:101], v[102:105], off
	global_store_dwordx2 v[106:107], v[96:97], off
	v_mul_f32_e32 v96, v103, v103
	v_mul_f32_e32 v97, v105, v105
	v_fmac_f32_e32 v96, v102, v102
	v_fmac_f32_e32 v97, v104, v104
	v_add_f32_e32 v106, v96, v97
	s_waitcnt vmcnt(30)
	v_mov_b64_e32 v[102:103], v[174:175]
	v_mov_b64_e32 v[104:105], v[176:177]
	v_pk_fma_f32 v[92:93], v[92:93], 0.5, v[104:105] op_sel_hi:[1,0,1]
	v_pk_fma_f32 v[90:91], v[90:91], 0.5, v[102:103] op_sel_hi:[1,0,1]
	global_store_dwordx4 v[100:101], v[90:93], off offset:64
	v_cvt_pk_bf16_f32 v96, v90, v91
	v_or_b32_e32 v102, 32, v94
	v_mul_f32_e32 v91, v91, v91
	v_mov_b32_e32 v103, v95
	v_fmac_f32_e32 v91, v90, v90
	v_mul_f32_e32 v90, v93, v93
	v_cvt_pk_bf16_f32 v97, v92, v93
	v_lshl_add_u64 v[102:103], s[14:15], 0, v[102:103]
	v_fmac_f32_e32 v90, v92, v92
	global_store_dwordx2 v[102:103], v[96:97], off
	v_add_f32_e32 v90, v91, v90
	v_add_f32_e32 v96, v106, v90
	s_waitcnt vmcnt(31)
	v_mov_b64_e32 v[90:91], v[186:187]
	v_mov_b64_e32 v[92:93], v[188:189]
	v_pk_fma_f32 v[88:89], v[88:89], 0.5, v[92:93] op_sel_hi:[1,0,1]
	v_pk_fma_f32 v[86:87], v[86:87], 0.5, v[90:91] op_sel_hi:[1,0,1]
	global_store_dwordx4 v[100:101], v[86:89], off offset:512
	v_cvt_pk_bf16_f32 v90, v86, v87
	v_or_b32_e32 v92, 0x100, v94
	v_mul_f32_e32 v87, v87, v87
	v_mov_b32_e32 v93, v95
	v_fmac_f32_e32 v87, v86, v86
	v_mul_f32_e32 v86, v89, v89
	v_cvt_pk_bf16_f32 v91, v88, v89
	v_lshl_add_u64 v[92:93], s[14:15], 0, v[92:93]
	v_fmac_f32_e32 v86, v88, v88
	global_store_dwordx2 v[92:93], v[90:91], off
	v_add_f32_e32 v86, v87, v86
	v_add_f32_e32 v90, v96, v86
	v_or_b32_e32 v94, 0x120, v94
	s_waitcnt vmcnt(32)
	v_mov_b64_e32 v[86:87], v[240:241]
	v_mov_b64_e32 v[88:89], v[242:243]
	v_pk_fma_f32 v[84:85], v[84:85], 0.5, v[88:89] op_sel_hi:[1,0,1]
	v_pk_fma_f32 v[82:83], v[82:83], 0.5, v[86:87] op_sel_hi:[1,0,1]
	global_store_dwordx4 v[100:101], v[82:85], off offset:576
	v_cvt_pk_bf16_f32 v86, v82, v83
	v_cvt_pk_bf16_f32 v87, v84, v85
	v_mul_f32_e32 v83, v83, v83
	v_fmac_f32_e32 v83, v82, v82
	v_mul_f32_e32 v82, v85, v85
	v_fmac_f32_e32 v82, v84, v84
	v_add_f32_e32 v82, v83, v82
	v_add_f32_e32 v82, v90, v82
	ds_bpermute_b32 v83, v162, v82
	v_lshl_add_u64 v[88:89], s[14:15], 0, v[94:95]
	global_store_dwordx2 v[88:89], v[86:87], off
	s_waitcnt lgkmcnt(0)
	v_add_f32_e32 v82, v82, v83
	ds_bpermute_b32 v83, v160, v82
	s_and_saveexec_b64 s[22:23], s[4:5]
	s_cbranch_execz .LBB0_1687
	v_lshlrev_b64 v[84:85], 6, v[98:99]
	v_lshl_add_u64 v[84:85], s[66:67], 0, v[84:85]
	v_lshl_add_u64 v[84:85], s[20:21], 2, v[84:85]
	s_lshl_b32 s68, s39, 2
	v_lshl_add_u64 v[84:85], v[84:85], 0, s[68:69]
	s_waitcnt lgkmcnt(0)
	v_add_f32_e32 v82, v82, v83
	global_store_dword v[84:85], v82, off
.LBB0_1687:
	s_or_b64 exec, exec, s[22:23]
	v_or_b32_e32 v82, 48, v138
	s_waitcnt lgkmcnt(0)
	v_ashrrev_i32_e32 v83, 31, v82
	v_lshlrev_b64 v[84:85], 10, v[82:83]
	v_lshl_add_u64 v[90:91], v[84:85], 0, v[136:137]
	v_lshl_add_u64 v[84:85], v[90:91], 2, s[10:11]
	s_mov_b64 s[22:23], 0x90000
	v_lshl_add_u64 v[206:207], v[204:205], 0, s[22:23]
	global_load_dwordx4 v[170:173], v[206:207], off
	global_load_dwordx4 v[174:177], v[206:207], off offset:64
	global_load_dwordx4 v[186:189], v[206:207], off offset:512
	global_load_dwordx4 v[240:243], v[206:207], off offset:576
	s_waitcnt vmcnt(29)
	v_mov_b64_e32 v[86:87], v[208:209]
	v_mov_b64_e32 v[88:89], v[210:211]
	v_pk_fma_f32 v[88:89], v[80:81], 0.5, v[88:89] op_sel_hi:[1,0,1]
	v_pk_fma_f32 v[86:87], v[78:79], 0.5, v[86:87] op_sel_hi:[1,0,1]
	v_lshlrev_b64 v[78:79], 1, v[90:91]
	v_cvt_pk_bf16_f32 v80, v86, v87
	v_cvt_pk_bf16_f32 v81, v88, v89
	v_lshl_add_u64 v[90:91], s[14:15], 0, v[78:79]
	global_store_dwordx4 v[84:85], v[86:89], off
	global_store_dwordx2 v[90:91], v[80:81], off
	v_mul_f32_e32 v80, v87, v87
	v_mul_f32_e32 v81, v89, v89
	v_fmac_f32_e32 v80, v86, v86
	v_fmac_f32_e32 v81, v88, v88
	v_add_f32_e32 v90, v80, v81
	s_waitcnt vmcnt(30)
	v_mov_b64_e32 v[86:87], v[212:213]
	v_mov_b64_e32 v[88:89], v[214:215]
	v_pk_fma_f32 v[76:77], v[76:77], 0.5, v[88:89] op_sel_hi:[1,0,1]
	v_pk_fma_f32 v[74:75], v[74:75], 0.5, v[86:87] op_sel_hi:[1,0,1]
	global_store_dwordx4 v[84:85], v[74:77], off offset:64
	v_cvt_pk_bf16_f32 v80, v74, v75
	v_or_b32_e32 v86, 32, v78
	v_mul_f32_e32 v75, v75, v75
	v_mov_b32_e32 v87, v79
	v_fmac_f32_e32 v75, v74, v74
	v_mul_f32_e32 v74, v77, v77
	v_cvt_pk_bf16_f32 v81, v76, v77
	v_lshl_add_u64 v[86:87], s[14:15], 0, v[86:87]
	v_fmac_f32_e32 v74, v76, v76
	global_store_dwordx2 v[86:87], v[80:81], off
	v_add_f32_e32 v74, v75, v74
	v_add_f32_e32 v80, v90, v74
	s_waitcnt vmcnt(31)
	v_mov_b64_e32 v[74:75], v[216:217]
	v_mov_b64_e32 v[76:77], v[218:219]
	v_pk_fma_f32 v[72:73], v[72:73], 0.5, v[76:77] op_sel_hi:[1,0,1]
	v_pk_fma_f32 v[70:71], v[70:71], 0.5, v[74:75] op_sel_hi:[1,0,1]
	global_store_dwordx4 v[84:85], v[70:73], off offset:512
	v_cvt_pk_bf16_f32 v74, v70, v71
	v_or_b32_e32 v76, 0x100, v78
	v_mul_f32_e32 v71, v71, v71
	v_mov_b32_e32 v77, v79
	v_fmac_f32_e32 v71, v70, v70
	v_mul_f32_e32 v70, v73, v73
	v_cvt_pk_bf16_f32 v75, v72, v73
	v_lshl_add_u64 v[76:77], s[14:15], 0, v[76:77]
	v_fmac_f32_e32 v70, v72, v72
	global_store_dwordx2 v[76:77], v[74:75], off
	v_add_f32_e32 v70, v71, v70
	v_add_f32_e32 v74, v80, v70
	v_or_b32_e32 v78, 0x120, v78
	s_waitcnt vmcnt(32)
	v_mov_b64_e32 v[70:71], v[220:221]
	v_mov_b64_e32 v[72:73], v[222:223]
	v_pk_fma_f32 v[68:69], v[68:69], 0.5, v[72:73] op_sel_hi:[1,0,1]
	v_pk_fma_f32 v[66:67], v[66:67], 0.5, v[70:71] op_sel_hi:[1,0,1]
	global_store_dwordx4 v[84:85], v[66:69], off offset:576
	v_cvt_pk_bf16_f32 v70, v66, v67
	v_cvt_pk_bf16_f32 v71, v68, v69
	v_mul_f32_e32 v67, v67, v67
	v_fmac_f32_e32 v67, v66, v66
	v_mul_f32_e32 v66, v69, v69
	v_fmac_f32_e32 v66, v68, v68
	v_add_f32_e32 v66, v67, v66
	v_add_f32_e32 v66, v74, v66
	ds_bpermute_b32 v67, v162, v66
	v_lshl_add_u64 v[72:73], s[14:15], 0, v[78:79]
	global_store_dwordx2 v[72:73], v[70:71], off
	s_waitcnt lgkmcnt(0)
	v_add_f32_e32 v66, v66, v67
	ds_bpermute_b32 v67, v160, v66
	s_and_saveexec_b64 s[22:23], s[4:5]
	s_cbranch_execz .LBB0_1689
	v_lshlrev_b64 v[68:69], 6, v[82:83]
	v_lshl_add_u64 v[68:69], s[66:67], 0, v[68:69]
	v_lshl_add_u64 v[68:69], s[20:21], 2, v[68:69]
	s_lshl_b32 s68, s39, 2
	v_lshl_add_u64 v[68:69], v[68:69], 0, s[68:69]
	s_waitcnt lgkmcnt(0)
	v_add_f32_e32 v66, v66, v67
	global_store_dword v[68:69], v66, off
.LBB0_1689:
	s_or_b64 exec, exec, s[22:23]
	v_add_u32_e32 v66, 0x80, v138
	s_waitcnt lgkmcnt(0)
	v_ashrrev_i32_e32 v67, 31, v66
	v_lshlrev_b64 v[68:69], 10, v[66:67]
	v_lshl_add_u64 v[74:75], v[68:69], 0, v[136:137]
	v_lshl_add_u64 v[68:69], v[74:75], 2, s[10:11]
	s_mov_b64 s[22:23], 0xa0000
	v_lshl_add_u64 v[206:207], v[204:205], 0, s[22:23]
	global_load_dwordx4 v[208:211], v[206:207], off
	global_load_dwordx4 v[212:215], v[206:207], off offset:64
	global_load_dwordx4 v[216:219], v[206:207], off offset:512
	global_load_dwordx4 v[220:223], v[206:207], off offset:576
	s_waitcnt vmcnt(29)
	v_mov_b64_e32 v[70:71], v[224:225]
	v_mov_b64_e32 v[72:73], v[226:227]
	v_pk_fma_f32 v[72:73], v[64:65], 0.5, v[72:73] op_sel_hi:[1,0,1]
	v_pk_fma_f32 v[70:71], v[62:63], 0.5, v[70:71] op_sel_hi:[1,0,1]
	v_lshlrev_b64 v[62:63], 1, v[74:75]
	v_cvt_pk_bf16_f32 v64, v70, v71
	v_cvt_pk_bf16_f32 v65, v72, v73
	v_lshl_add_u64 v[74:75], s[14:15], 0, v[62:63]
	global_store_dwordx4 v[68:69], v[70:73], off
	global_store_dwordx2 v[74:75], v[64:65], off
	v_mul_f32_e32 v64, v71, v71
	v_mul_f32_e32 v65, v73, v73
	v_fmac_f32_e32 v64, v70, v70
	v_fmac_f32_e32 v65, v72, v72
	v_add_f32_e32 v74, v64, v65
	s_waitcnt vmcnt(30)
	v_mov_b64_e32 v[70:71], v[228:229]
	v_mov_b64_e32 v[72:73], v[230:231]
	v_pk_fma_f32 v[60:61], v[60:61], 0.5, v[72:73] op_sel_hi:[1,0,1]
	v_pk_fma_f32 v[58:59], v[58:59], 0.5, v[70:71] op_sel_hi:[1,0,1]
	global_store_dwordx4 v[68:69], v[58:61], off offset:64
	v_cvt_pk_bf16_f32 v64, v58, v59
	v_or_b32_e32 v70, 32, v62
	v_mul_f32_e32 v59, v59, v59
	v_mov_b32_e32 v71, v63
	v_fmac_f32_e32 v59, v58, v58
	v_mul_f32_e32 v58, v61, v61
	v_cvt_pk_bf16_f32 v65, v60, v61
	v_lshl_add_u64 v[70:71], s[14:15], 0, v[70:71]
	v_fmac_f32_e32 v58, v60, v60
	global_store_dwordx2 v[70:71], v[64:65], off
	v_add_f32_e32 v58, v59, v58
	v_add_f32_e32 v64, v74, v58
	s_waitcnt vmcnt(31)
	v_mov_b64_e32 v[58:59], v[232:233]
	v_mov_b64_e32 v[60:61], v[234:235]
	v_pk_fma_f32 v[56:57], v[56:57], 0.5, v[60:61] op_sel_hi:[1,0,1]
	v_pk_fma_f32 v[54:55], v[54:55], 0.5, v[58:59] op_sel_hi:[1,0,1]
	global_store_dwordx4 v[68:69], v[54:57], off offset:512
	v_cvt_pk_bf16_f32 v58, v54, v55
	v_or_b32_e32 v60, 0x100, v62
	v_mul_f32_e32 v55, v55, v55
	v_mov_b32_e32 v61, v63
	v_fmac_f32_e32 v55, v54, v54
	v_mul_f32_e32 v54, v57, v57
	v_cvt_pk_bf16_f32 v59, v56, v57
	v_lshl_add_u64 v[60:61], s[14:15], 0, v[60:61]
	v_fmac_f32_e32 v54, v56, v56
	global_store_dwordx2 v[60:61], v[58:59], off
	v_add_f32_e32 v54, v55, v54
	v_add_f32_e32 v58, v64, v54
	v_or_b32_e32 v62, 0x120, v62
	s_waitcnt vmcnt(32)
	v_mov_b64_e32 v[54:55], v[236:237]
	v_mov_b64_e32 v[56:57], v[238:239]
	v_pk_fma_f32 v[52:53], v[52:53], 0.5, v[56:57] op_sel_hi:[1,0,1]
	v_pk_fma_f32 v[50:51], v[50:51], 0.5, v[54:55] op_sel_hi:[1,0,1]
	global_store_dwordx4 v[68:69], v[50:53], off offset:576
	v_cvt_pk_bf16_f32 v54, v50, v51
	v_cvt_pk_bf16_f32 v55, v52, v53
	v_mul_f32_e32 v51, v51, v51
	v_fmac_f32_e32 v51, v50, v50
	v_mul_f32_e32 v50, v53, v53
	v_fmac_f32_e32 v50, v52, v52
	v_add_f32_e32 v50, v51, v50
	v_add_f32_e32 v50, v58, v50
	ds_bpermute_b32 v51, v162, v50
	v_lshl_add_u64 v[56:57], s[14:15], 0, v[62:63]
	global_store_dwordx2 v[56:57], v[54:55], off
	s_waitcnt lgkmcnt(0)
	v_add_f32_e32 v50, v50, v51
	ds_bpermute_b32 v51, v160, v50
	s_and_saveexec_b64 s[22:23], s[4:5]
	s_cbranch_execz .LBB0_1691
	v_lshlrev_b64 v[52:53], 6, v[66:67]
	v_lshl_add_u64 v[52:53], s[66:67], 0, v[52:53]
	v_lshl_add_u64 v[52:53], s[20:21], 2, v[52:53]
	s_lshl_b32 s68, s39, 2
	v_lshl_add_u64 v[52:53], v[52:53], 0, s[68:69]
	s_waitcnt lgkmcnt(0)
	v_add_f32_e32 v50, v50, v51
	global_store_dword v[52:53], v50, off
.LBB0_1691:
	s_or_b64 exec, exec, s[22:23]
	v_add_u32_e32 v50, 0x90, v138
	s_waitcnt lgkmcnt(0)
	v_ashrrev_i32_e32 v51, 31, v50
	v_lshlrev_b64 v[52:53], 10, v[50:51]
	v_lshl_add_u64 v[58:59], v[52:53], 0, v[136:137]
	v_lshl_add_u64 v[52:53], v[58:59], 2, s[10:11]
	s_mov_b64 s[22:23], 0xb0000
	v_lshl_add_u64 v[206:207], v[204:205], 0, s[22:23]
	global_load_dwordx4 v[224:227], v[206:207], off
	global_load_dwordx4 v[228:231], v[206:207], off offset:64
	global_load_dwordx4 v[232:235], v[206:207], off offset:512
	global_load_dwordx4 v[236:239], v[206:207], off offset:576
	s_waitcnt vmcnt(29)
	v_mov_b64_e32 v[54:55], v[170:171]
	v_mov_b64_e32 v[56:57], v[172:173]
	v_pk_fma_f32 v[56:57], v[48:49], 0.5, v[56:57] op_sel_hi:[1,0,1]
	v_pk_fma_f32 v[54:55], v[46:47], 0.5, v[54:55] op_sel_hi:[1,0,1]
	v_lshlrev_b64 v[46:47], 1, v[58:59]
	v_cvt_pk_bf16_f32 v48, v54, v55
	v_cvt_pk_bf16_f32 v49, v56, v57
	v_lshl_add_u64 v[58:59], s[14:15], 0, v[46:47]
	global_store_dwordx4 v[52:53], v[54:57], off
	global_store_dwordx2 v[58:59], v[48:49], off
	v_mul_f32_e32 v48, v55, v55
	v_mul_f32_e32 v49, v57, v57
	v_fmac_f32_e32 v48, v54, v54
	v_fmac_f32_e32 v49, v56, v56
	v_add_f32_e32 v58, v48, v49
	s_waitcnt vmcnt(30)
	v_mov_b64_e32 v[54:55], v[174:175]
	v_mov_b64_e32 v[56:57], v[176:177]
	v_pk_fma_f32 v[44:45], v[44:45], 0.5, v[56:57] op_sel_hi:[1,0,1]
	v_pk_fma_f32 v[42:43], v[42:43], 0.5, v[54:55] op_sel_hi:[1,0,1]
	global_store_dwordx4 v[52:53], v[42:45], off offset:64
	v_cvt_pk_bf16_f32 v48, v42, v43
	v_or_b32_e32 v54, 32, v46
	v_mul_f32_e32 v43, v43, v43
	v_mov_b32_e32 v55, v47
	v_fmac_f32_e32 v43, v42, v42
	v_mul_f32_e32 v42, v45, v45
	v_cvt_pk_bf16_f32 v49, v44, v45
	v_lshl_add_u64 v[54:55], s[14:15], 0, v[54:55]
	v_fmac_f32_e32 v42, v44, v44
	global_store_dwordx2 v[54:55], v[48:49], off
	v_add_f32_e32 v42, v43, v42
	v_add_f32_e32 v48, v58, v42
	s_waitcnt vmcnt(31)
	v_mov_b64_e32 v[42:43], v[186:187]
	v_mov_b64_e32 v[44:45], v[188:189]
	v_pk_fma_f32 v[40:41], v[40:41], 0.5, v[44:45] op_sel_hi:[1,0,1]
	v_pk_fma_f32 v[38:39], v[38:39], 0.5, v[42:43] op_sel_hi:[1,0,1]
	global_store_dwordx4 v[52:53], v[38:41], off offset:512
	v_cvt_pk_bf16_f32 v42, v38, v39
	v_or_b32_e32 v44, 0x100, v46
	v_mul_f32_e32 v39, v39, v39
	v_mov_b32_e32 v45, v47
	v_fmac_f32_e32 v39, v38, v38
	v_mul_f32_e32 v38, v41, v41
	v_cvt_pk_bf16_f32 v43, v40, v41
	v_lshl_add_u64 v[44:45], s[14:15], 0, v[44:45]
	v_fmac_f32_e32 v38, v40, v40
	global_store_dwordx2 v[44:45], v[42:43], off
	v_add_f32_e32 v38, v39, v38
	v_add_f32_e32 v42, v48, v38
	v_or_b32_e32 v46, 0x120, v46
	s_waitcnt vmcnt(32)
	v_mov_b64_e32 v[38:39], v[240:241]
	v_mov_b64_e32 v[40:41], v[242:243]
	v_pk_fma_f32 v[36:37], v[36:37], 0.5, v[40:41] op_sel_hi:[1,0,1]
	v_pk_fma_f32 v[34:35], v[34:35], 0.5, v[38:39] op_sel_hi:[1,0,1]
	global_store_dwordx4 v[52:53], v[34:37], off offset:576
	v_cvt_pk_bf16_f32 v38, v34, v35
	v_cvt_pk_bf16_f32 v39, v36, v37
	v_mul_f32_e32 v35, v35, v35
	v_fmac_f32_e32 v35, v34, v34
	v_mul_f32_e32 v34, v37, v37
	v_fmac_f32_e32 v34, v36, v36
	v_add_f32_e32 v34, v35, v34
	v_add_f32_e32 v34, v42, v34
	ds_bpermute_b32 v35, v162, v34
	v_lshl_add_u64 v[40:41], s[14:15], 0, v[46:47]
	global_store_dwordx2 v[40:41], v[38:39], off
	s_waitcnt lgkmcnt(0)
	v_add_f32_e32 v34, v34, v35
	ds_bpermute_b32 v35, v160, v34
	s_and_saveexec_b64 s[22:23], s[4:5]
	s_cbranch_execz .LBB0_1693
	v_lshlrev_b64 v[36:37], 6, v[50:51]
	v_lshl_add_u64 v[36:37], s[66:67], 0, v[36:37]
	v_lshl_add_u64 v[36:37], s[20:21], 2, v[36:37]
	s_lshl_b32 s68, s39, 2
	v_lshl_add_u64 v[36:37], v[36:37], 0, s[68:69]
	s_waitcnt lgkmcnt(0)
	v_add_f32_e32 v34, v34, v35
	global_store_dword v[36:37], v34, off
.LBB0_1693:
	s_or_b64 exec, exec, s[22:23]
	v_add_u32_e32 v34, 0xa0, v138
	s_waitcnt lgkmcnt(0)
	v_ashrrev_i32_e32 v35, 31, v34
	v_lshlrev_b64 v[36:37], 10, v[34:35]
	v_lshl_add_u64 v[42:43], v[36:37], 0, v[136:137]
	v_lshl_add_u64 v[36:37], v[42:43], 2, s[10:11]
	s_waitcnt vmcnt(25)
	v_mov_b64_e32 v[38:39], v[208:209]
	v_mov_b64_e32 v[40:41], v[210:211]
	v_pk_fma_f32 v[40:41], v[32:33], 0.5, v[40:41] op_sel_hi:[1,0,1]
	v_pk_fma_f32 v[38:39], v[30:31], 0.5, v[38:39] op_sel_hi:[1,0,1]
	v_lshlrev_b64 v[30:31], 1, v[42:43]
	v_cvt_pk_bf16_f32 v32, v38, v39
	v_cvt_pk_bf16_f32 v33, v40, v41
	v_lshl_add_u64 v[42:43], s[14:15], 0, v[30:31]
	global_store_dwordx4 v[36:37], v[38:41], off
	global_store_dwordx2 v[42:43], v[32:33], off
	v_mul_f32_e32 v32, v39, v39
	v_mul_f32_e32 v33, v41, v41
	v_fmac_f32_e32 v32, v38, v38
	v_fmac_f32_e32 v33, v40, v40
	v_add_f32_e32 v42, v32, v33
	s_waitcnt vmcnt(26)
	v_mov_b64_e32 v[38:39], v[212:213]
	v_mov_b64_e32 v[40:41], v[214:215]
	v_pk_fma_f32 v[28:29], v[28:29], 0.5, v[40:41] op_sel_hi:[1,0,1]
	v_pk_fma_f32 v[26:27], v[26:27], 0.5, v[38:39] op_sel_hi:[1,0,1]
	global_store_dwordx4 v[36:37], v[26:29], off offset:64
	v_cvt_pk_bf16_f32 v32, v26, v27
	v_or_b32_e32 v38, 32, v30
	v_mul_f32_e32 v27, v27, v27
	v_mov_b32_e32 v39, v31
	v_fmac_f32_e32 v27, v26, v26
	v_mul_f32_e32 v26, v29, v29
	v_cvt_pk_bf16_f32 v33, v28, v29
	v_lshl_add_u64 v[38:39], s[14:15], 0, v[38:39]
	v_fmac_f32_e32 v26, v28, v28
	global_store_dwordx2 v[38:39], v[32:33], off
	v_add_f32_e32 v26, v27, v26
	v_add_f32_e32 v32, v42, v26
	s_waitcnt vmcnt(27)
	v_mov_b64_e32 v[26:27], v[216:217]
	v_mov_b64_e32 v[28:29], v[218:219]
	v_pk_fma_f32 v[24:25], v[24:25], 0.5, v[28:29] op_sel_hi:[1,0,1]
	v_pk_fma_f32 v[22:23], v[22:23], 0.5, v[26:27] op_sel_hi:[1,0,1]
	global_store_dwordx4 v[36:37], v[22:25], off offset:512
	v_cvt_pk_bf16_f32 v26, v22, v23
	v_or_b32_e32 v28, 0x100, v30
	v_mul_f32_e32 v23, v23, v23
	v_mov_b32_e32 v29, v31
	v_fmac_f32_e32 v23, v22, v22
	v_mul_f32_e32 v22, v25, v25
	v_cvt_pk_bf16_f32 v27, v24, v25
	v_lshl_add_u64 v[28:29], s[14:15], 0, v[28:29]
	v_fmac_f32_e32 v22, v24, v24
	global_store_dwordx2 v[28:29], v[26:27], off
	v_add_f32_e32 v22, v23, v22
	v_add_f32_e32 v26, v32, v22
	v_or_b32_e32 v30, 0x120, v30
	s_waitcnt vmcnt(28)
	v_mov_b64_e32 v[22:23], v[220:221]
	v_mov_b64_e32 v[24:25], v[222:223]
	v_pk_fma_f32 v[20:21], v[20:21], 0.5, v[24:25] op_sel_hi:[1,0,1]
	v_pk_fma_f32 v[18:19], v[18:19], 0.5, v[22:23] op_sel_hi:[1,0,1]
	global_store_dwordx4 v[36:37], v[18:21], off offset:576
	v_cvt_pk_bf16_f32 v22, v18, v19
	v_cvt_pk_bf16_f32 v23, v20, v21
	v_mul_f32_e32 v19, v19, v19
	v_fmac_f32_e32 v19, v18, v18
	v_mul_f32_e32 v18, v21, v21
	v_fmac_f32_e32 v18, v20, v20
	v_add_f32_e32 v18, v19, v18
	v_add_f32_e32 v18, v26, v18
	ds_bpermute_b32 v19, v162, v18
	v_lshl_add_u64 v[24:25], s[14:15], 0, v[30:31]
	global_store_dwordx2 v[24:25], v[22:23], off
	s_waitcnt lgkmcnt(0)
	v_add_f32_e32 v18, v18, v19
	ds_bpermute_b32 v19, v160, v18
	s_and_saveexec_b64 s[22:23], s[4:5]
	s_cbranch_execz .LBB0_1695
	v_lshlrev_b64 v[20:21], 6, v[34:35]
	v_lshl_add_u64 v[20:21], s[66:67], 0, v[20:21]
	v_lshl_add_u64 v[20:21], s[20:21], 2, v[20:21]
	s_lshl_b32 s68, s39, 2
	v_lshl_add_u64 v[20:21], v[20:21], 0, s[68:69]
	s_waitcnt lgkmcnt(0)
	v_add_f32_e32 v18, v18, v19
	global_store_dword v[20:21], v18, off
.LBB0_1695:
	s_or_b64 exec, exec, s[22:23]
	v_add_u32_e32 v18, 0xb0, v138
	s_waitcnt lgkmcnt(0)
	v_ashrrev_i32_e32 v19, 31, v18
	v_lshlrev_b64 v[20:21], 10, v[18:19]
	v_lshl_add_u64 v[26:27], v[20:21], 0, v[136:137]
	v_lshl_add_u64 v[20:21], v[26:27], 2, s[10:11]
	s_waitcnt vmcnt(21)
	v_mov_b64_e32 v[22:23], v[224:225]
	v_mov_b64_e32 v[24:25], v[226:227]
	v_pk_fma_f32 v[24:25], v[16:17], 0.5, v[24:25] op_sel_hi:[1,0,1]
	v_pk_fma_f32 v[22:23], v[14:15], 0.5, v[22:23] op_sel_hi:[1,0,1]
	v_lshlrev_b64 v[14:15], 1, v[26:27]
	v_cvt_pk_bf16_f32 v16, v22, v23
	v_cvt_pk_bf16_f32 v17, v24, v25
	v_lshl_add_u64 v[26:27], s[14:15], 0, v[14:15]
	global_store_dwordx4 v[20:21], v[22:25], off
	global_store_dwordx2 v[26:27], v[16:17], off
	v_mul_f32_e32 v16, v23, v23
	v_mul_f32_e32 v17, v25, v25
	v_fmac_f32_e32 v16, v22, v22
	v_fmac_f32_e32 v17, v24, v24
	v_add_f32_e32 v26, v16, v17
	s_waitcnt vmcnt(22)
	v_mov_b64_e32 v[22:23], v[228:229]
	v_mov_b64_e32 v[24:25], v[230:231]
	v_pk_fma_f32 v[12:13], v[12:13], 0.5, v[24:25] op_sel_hi:[1,0,1]
	v_pk_fma_f32 v[10:11], v[10:11], 0.5, v[22:23] op_sel_hi:[1,0,1]
	global_store_dwordx4 v[20:21], v[10:13], off offset:64
	v_cvt_pk_bf16_f32 v16, v10, v11
	v_or_b32_e32 v22, 32, v14
	v_mul_f32_e32 v11, v11, v11
	v_mov_b32_e32 v23, v15
	v_fmac_f32_e32 v11, v10, v10
	v_mul_f32_e32 v10, v13, v13
	v_cvt_pk_bf16_f32 v17, v12, v13
	v_lshl_add_u64 v[22:23], s[14:15], 0, v[22:23]
	v_fmac_f32_e32 v10, v12, v12
	global_store_dwordx2 v[22:23], v[16:17], off
	v_add_f32_e32 v10, v11, v10
	v_add_f32_e32 v16, v26, v10
	s_waitcnt vmcnt(23)
	v_mov_b64_e32 v[10:11], v[232:233]
	v_mov_b64_e32 v[12:13], v[234:235]
	v_pk_fma_f32 v[8:9], v[8:9], 0.5, v[12:13] op_sel_hi:[1,0,1]
	v_pk_fma_f32 v[6:7], v[6:7], 0.5, v[10:11] op_sel_hi:[1,0,1]
	global_store_dwordx4 v[20:21], v[6:9], off offset:512
	v_cvt_pk_bf16_f32 v10, v6, v7
	v_or_b32_e32 v12, 0x100, v14
	v_mul_f32_e32 v7, v7, v7
	v_mov_b32_e32 v13, v15
	v_fmac_f32_e32 v7, v6, v6
	v_mul_f32_e32 v6, v9, v9
	v_cvt_pk_bf16_f32 v11, v8, v9
	v_lshl_add_u64 v[12:13], s[14:15], 0, v[12:13]
	v_fmac_f32_e32 v6, v8, v8
	global_store_dwordx2 v[12:13], v[10:11], off
	v_add_f32_e32 v6, v7, v6
	v_add_f32_e32 v10, v16, v6
	v_or_b32_e32 v14, 0x120, v14
	s_waitcnt vmcnt(24)
	v_mov_b64_e32 v[6:7], v[236:237]
	v_mov_b64_e32 v[8:9], v[238:239]
	v_pk_fma_f32 v[4:5], v[4:5], 0.5, v[8:9] op_sel_hi:[1,0,1]
	v_pk_fma_f32 v[2:3], v[2:3], 0.5, v[6:7] op_sel_hi:[1,0,1]
	global_store_dwordx4 v[20:21], v[2:5], off offset:576
	v_cvt_pk_bf16_f32 v6, v2, v3
	v_cvt_pk_bf16_f32 v7, v4, v5
	v_mul_f32_e32 v3, v3, v3
	v_fmac_f32_e32 v3, v2, v2
	v_mul_f32_e32 v2, v5, v5
	v_fmac_f32_e32 v2, v4, v4
	v_add_f32_e32 v2, v3, v2
	v_add_f32_e32 v2, v10, v2
	ds_bpermute_b32 v3, v162, v2
	v_lshl_add_u64 v[8:9], s[14:15], 0, v[14:15]
	global_store_dwordx2 v[8:9], v[6:7], off
	s_waitcnt lgkmcnt(0)
	v_add_f32_e32 v2, v2, v3
	ds_bpermute_b32 v3, v160, v2
	s_and_saveexec_b64 s[22:23], s[4:5]
	s_cbranch_execz .LBB0_1697
	v_lshlrev_b64 v[4:5], 6, v[18:19]
	v_lshl_add_u64 v[4:5], s[66:67], 0, v[4:5]
	v_lshl_add_u64 v[4:5], s[20:21], 2, v[4:5]
	s_lshl_b32 s68, s39, 2
	v_lshl_add_u64 v[4:5], v[4:5], 0, s[68:69]
	s_waitcnt lgkmcnt(0)
	v_add_f32_e32 v2, v2, v3
	global_store_dword v[4:5], v2, off
